# hand-written SSM scan loop: one dword load+store per step, SGPR bases, 24-step prefetch, pk_fma recurrence
# speedup vs baseline: 1.0052x; 1.0021x over previous
; #define SCAN_LOAD(buf, b) do { _Pragma("unroll") for (int k = 0; k < 16; ++k) { sr[buf][k] = __uint_as_float((unsigned)Sp[((b) + k) * sS] << 16); si[buf][k] = __uint_as_float((unsigned)Sp[((b) + k) * sS + 64] << 16); } } while (0)
; __device__ __forceinline__ void scan_merge_phase(const Params& p, int G) {
;     ...
;         const float are = p.in[4][(dir * 64 + g) * 64 + lane], aim = p.in[5][(dir * 64 + g) * 64 + lane], dt = expf(p.in[6][dir * 64 + g]);
;         const float mag = expf(16.0f * are * dt); float sn, cs; sincosf(16.0f * aim * dt, &sn, &cs);
;         const float ar = mag * cs, ai = mag * sn;
;         float hr = 0.f, hi = 0.f;
;         const int nstart = dir == 0 ? n0 : n0 + len - 1; const long step = dir == 0 ? 1 : -1;
;         const bf16_t* Sp = S + ((size_t)g * NCHUNK + nstart) * 256 + dir * 128 + lane;
;         bf16_t* Ap = assm + ((size_t)g * NCHUNK + nstart) * 512 + 256 + dir * 128 + lane;
;         const long sS = step * 256, sA = step * 512;
;         float sr[2][16], si[2][16];
;     ...
;         SCAN_LOAD(0, 0);
.LBB0_117:
	s_andn2_saveexec_b64 s[0:1], s[14:15]
	v_mul_f32_e64 v0, |v3|, s87
	v_rndne_f32_e32 v0, v0
	v_cvt_i32_f32_e32 v14, v0
	v_fma_f32 v13, v0, s91, |v3|
	v_fmac_f32_e32 v13, 0xb3a22168, v0
	v_fmac_f32_e32 v13, 0xa7c234c4, v0
	s_or_b64 exec, exec, s[0:1]
	v_ashrrev_i32_e32 v8, 7, v97
	v_cmp_gt_i32_e32 vcc, 4, v8
	v_bfe_u32 v7, v97, 6, 1
	v_bfe_i32 v19, v97, 6, 1
	v_cndmask_b32_e32 v98, v206, v207, vcc
	v_add_u32_e32 v15, -1, v98
	v_lshlrev_b32_e32 v0, 8, v7
	v_cmp_eq_u32_e32 vcc, 0, v7
	v_and_b32_e32 v7, v19, v15
	v_and_b32_e32 v9, 63, v97
	v_lshl_add_u32 v8, v8, 9, v7
	v_mul_u32_u24_e32 v16, 0xc00, v9
	v_mov_b32_e32 v17, v1
	v_ashrrev_i32_e32 v9, 31, v8
	v_lshl_add_u64 v[22:23], v[8:9], 0, v[16:17]
	v_lshlrev_b64 v[20:21], 9, v[22:23]
	v_lshl_add_u64 v[8:9], s[92:93], 0, v[20:21]
	v_cndmask_b32_e64 v18, -1, 1, vcc
	v_lshl_add_u64 v[8:9], v[8:9], 0, v[0:1]
	v_mov_b32_e32 v7, v1
	v_lshl_add_u64 v[16:17], v[8:9], 0, v[6:7]
	v_lshlrev_b64 v[8:9], 9, v[18:19]
	v_lshl_add_u64 v[24:25], v[16:17], 0, v[8:9]
	v_lshl_add_u64 v[26:27], v[24:25], 0, v[8:9]
	v_lshl_add_u64 v[28:29], v[26:27], 0, v[8:9]
	global_load_ushort v7, v[24:25], off
	global_load_ushort v15, v[16:17], off
	global_load_ushort v30, v[24:25], off offset:128
	global_load_ushort v31, v[28:29], off
	global_load_ushort v32, v[26:27], off
	global_load_ushort v33, v[28:29], off offset:128
	global_load_ushort v34, v[26:27], off offset:128
	global_load_ushort v35, v[16:17], off offset:128
	v_lshl_add_u64 v[16:17], v[28:29], 0, v[8:9]
	v_lshl_add_u64 v[24:25], v[16:17], 0, v[8:9]
	v_lshl_add_u64 v[26:27], v[24:25], 0, v[8:9]
	v_lshl_add_u64 v[28:29], v[26:27], 0, v[8:9]
	global_load_ushort v36, v[24:25], off
	global_load_ushort v37, v[16:17], off
	global_load_ushort v38, v[24:25], off offset:128
	global_load_ushort v39, v[28:29], off
	global_load_ushort v40, v[26:27], off
	global_load_ushort v41, v[28:29], off offset:128
	global_load_ushort v42, v[26:27], off offset:128
	global_load_ushort v43, v[16:17], off offset:128
	v_lshl_add_u64 v[16:17], v[28:29], 0, v[8:9]
	v_lshl_add_u64 v[24:25], v[16:17], 0, v[8:9]
	v_lshl_add_u64 v[26:27], v[24:25], 0, v[8:9]
	v_lshl_add_u64 v[28:29], v[26:27], 0, v[8:9]
	global_load_ushort v44, v[24:25], off
	global_load_ushort v45, v[16:17], off
	global_load_ushort v46, v[24:25], off offset:128
	global_load_ushort v47, v[28:29], off
	global_load_ushort v48, v[26:27], off
	global_load_ushort v49, v[28:29], off offset:128
	global_load_ushort v50, v[26:27], off offset:128
	global_load_ushort v51, v[16:17], off offset:128
	v_lshl_add_u64 v[16:17], v[28:29], 0, v[8:9]
	v_lshl_add_u64 v[24:25], v[16:17], 0, v[8:9]
	v_lshl_add_u64 v[26:27], v[24:25], 0, v[8:9]
	v_lshl_add_u64 v[28:29], v[26:27], 0, v[8:9]
	global_load_ushort v52, v[24:25], off
	global_load_ushort v53, v[16:17], off
	s_nop 0
	global_load_ushort v24, v[24:25], off offset:128
	s_nop 0
	global_load_ushort v25, v[26:27], off
	s_nop 0
	global_load_ushort v26, v[26:27], off offset:128
	s_nop 0
	global_load_ushort v27, v[28:29], off
	s_nop 0
	global_load_ushort v17, v[16:17], off offset:128
	s_nop 0
	global_load_ushort v29, v[28:29], off offset:128
	s_waitcnt vmcnt(32)
	v_mul_f32_e32 v11, 0x41800000, v11
	v_mul_f32_e32 v11, v11, v12
	v_mul_f32_e32 v12, 0x3fb8aa3b, v11
	v_fma_f32 v16, v11, s89, -v12
	v_rndne_f32_e32 v28, v12
	v_fmac_f32_e32 v16, 0x32a5705f, v11
	v_sub_f32_e32 v12, v12, v28
	v_add_f32_e32 v12, v12, v16
	v_exp_f32_e32 v12, v12
	v_cvt_i32_f32_e32 v16, v28
	v_cmp_ngt_f32_e32 vcc, s4, v11
	v_xor_b32_e32 v10, v10, v3
	s_movk_i32 s0, 0x4200
	v_ldexp_f32 v12, v12, v16
	v_cndmask_b32_e32 v12, 0, v12, vcc
	v_cmp_nlt_f32_e32 vcc, s90, v11
	v_lshlrev_b64 v[22:23], 10, v[22:23]
	v_or_b32_e32 v22, v22, v0
	v_cndmask_b32_e32 v11, v203, v12, vcc
	v_mul_f32_e32 v12, v13, v13
	v_fmamk_f32 v28, v12, 0xb94c1982, v199
	v_fmaak_f32 v28, v12, v28, 0xbe2aaa9d
	v_mul_f32_e32 v28, v12, v28
	v_fmac_f32_e32 v13, v13, v28
	v_fmamk_f32 v28, v12, 0x37d75334, v200
	v_fmaak_f32 v28, v12, v28, 0x3d2aabf7
	v_fmaak_f32 v28, v12, v28, 0xbf000004
	v_fma_f32 v12, v12, v28, 1.0
	v_lshlrev_b32_e32 v28, 30, v14
	v_and_b32_e32 v14, 1, v14
	v_cmp_eq_u32_e32 vcc, 0, v14
	v_and_b32_e32 v54, 0x80000000, v28
	v_mov_b32_e32 v16, 0
	v_cndmask_b32_e32 v14, v12, v13, vcc
	v_xor_b32_e32 v10, v10, v14
	v_xor_b32_e32 v14, v10, v54
	v_xor_b32_e32 v10, 0x80000000, v13
	v_cndmask_b32_e32 v10, v10, v12, vcc
	v_cmp_class_f32_e64 vcc, v3, s5
	v_bitop3_b32 v10, v10, v28, s3 bitop3:0x78
	v_lshlrev_b64 v[64:65], 15, v[18:19]
	v_cndmask_b32_e32 v12, v208, v14, vcc
	v_cndmask_b32_e32 v3, v208, v10, vcc
	v_mul_f32_e32 v10, v11, v3
	v_mul_f32_e32 v12, v11, v12
	v_mov_b32_e32 v11, v10
	v_mov_b32_e32 v13, v12
	v_lshlrev_b64 v[68:69], 10, v[18:19]
	s_mov_b32 s14, 32
	s_mov_b64 s[6:7], 0
	s_waitcnt vmcnt(31)
	v_lshlrev_b32_e32 v100, 16, v7
	s_waitcnt vmcnt(30)
	v_lshlrev_b32_e32 v99, 16, v15
	v_lshlrev_b64 v[14:15], 14, v[18:19]
	s_waitcnt vmcnt(29)
	v_lshlrev_b32_e32 v28, 16, v30
	s_waitcnt vmcnt(28)
	v_lshlrev_b32_e32 v102, 16, v31
	s_waitcnt vmcnt(27)
	v_lshlrev_b32_e32 v101, 16, v32
	s_waitcnt vmcnt(26)
	v_lshlrev_b32_e32 v70, 16, v33
	s_waitcnt vmcnt(24)
	v_lshlrev_b32_e32 v3, 16, v35
	v_lshlrev_b32_e32 v7, 16, v34
	s_waitcnt vmcnt(22)
	v_lshlrev_b32_e32 v103, 16, v37
	v_lshlrev_b32_e32 v104, 16, v36
	s_waitcnt vmcnt(21)
	v_lshlrev_b32_e32 v71, 16, v38
	s_waitcnt vmcnt(20)
	v_lshlrev_b32_e32 v106, 16, v39
	s_waitcnt vmcnt(19)
	v_lshlrev_b32_e32 v105, 16, v40
	s_waitcnt vmcnt(18)
	v_lshlrev_b32_e32 v73, 16, v41
	s_waitcnt vmcnt(16)
	v_lshlrev_b32_e32 v72, 16, v43
	v_lshlrev_b32_e32 v74, 16, v42
	s_waitcnt vmcnt(5)
	v_lshlrev_b32_e32 v79, 16, v24
	s_waitcnt vmcnt(4)
; #define SCAN_LOAD(buf, b) do { _Pragma("unroll") for (int k = 0; k < 16; ++k) { sr[buf][k] = __uint_as_float((unsigned)Sp[((b) + k) * sS] << 16); si[buf][k] = __uint_as_float((unsigned)Sp[((b) + k) * sS + 64] << 16); } } while (0)
; __device__ __forceinline__ void scan_merge_phase(const Params& p, int G) {
;     ...
;     for (int item = (tid >> 6) * G + blockIdx.x; item < 640; item += 8 * G) {
;         const int g = item & 63, dir = (item >> 6) & 1, seq = item >> 7;
;         const int n0 = seq < 4 ? seq * 512 : 2048, len = seq < 4 ? 512 : 1024;
;         const float are = p.in[4][(dir * 64 + g) * 64 + lane], aim = p.in[5][(dir * 64 + g) * 64 + lane], dt = expf(p.in[6][dir * 64 + g]);
;         const float mag = expf(16.0f * are * dt); float sn, cs; sincosf(16.0f * aim * dt, &sn, &cs);
;         const float ar = mag * cs, ai = mag * sn;
;         float hr = 0.f, hi = 0.f;
;         const int nstart = dir == 0 ? n0 : n0 + len - 1; const long step = dir == 0 ? 1 : -1;
;         const bf16_t* Sp = S + ((size_t)g * NCHUNK + nstart) * 256 + dir * 128 + lane;
;         bf16_t* Ap = assm + ((size_t)g * NCHUNK + nstart) * 512 + 256 + dir * 128 + lane;
;         const long sS = step * 256, sA = step * 512;
;         float sr[2][16], si[2][16];
;     ...
;         SCAN_LOAD(0, 0);
	v_lshlrev_b32_e32 v113, 16, v25
	v_lshl_add_u64 v[24:25], v[14:15], 0, v[20:21]
	v_or_b32_e32 v24, v24, v0
	v_lshl_add_u64 v[30:31], s[48:49], 0, v[24:25]
	v_mad_i64_i32 v[24:25], s[0:1], v18, s0, v[20:21]
	v_or_b32_e32 v24, v24, v0
	s_movk_i32 s0, 0x4400
	v_lshl_add_u64 v[32:33], s[48:49], 0, v[24:25]
	v_mad_i64_i32 v[24:25], s[0:1], v18, s0, v[20:21]
	v_or_b32_e32 v24, v24, v0
	s_movk_i32 s0, 0x4600
	v_lshl_add_u64 v[34:35], s[48:49], 0, v[24:25]
	v_mad_i64_i32 v[24:25], s[0:1], v18, s0, v[20:21]
	v_or_b32_e32 v24, v24, v0
	s_movk_i32 s0, 0x4800
	v_lshl_add_u64 v[36:37], s[48:49], 0, v[24:25]
	v_mad_i64_i32 v[24:25], s[0:1], v18, s0, v[20:21]
	v_or_b32_e32 v24, v24, v0
	s_movk_i32 s0, 0x4a00
	v_lshl_add_u64 v[38:39], s[48:49], 0, v[24:25]
	v_mad_i64_i32 v[24:25], s[0:1], v18, s0, v[20:21]
	v_or_b32_e32 v24, v24, v0
	s_movk_i32 s0, 0x4c00
	v_lshl_add_u64 v[40:41], s[48:49], 0, v[24:25]
	v_mad_i64_i32 v[24:25], s[0:1], v18, s0, v[20:21]
	v_or_b32_e32 v24, v24, v0
	s_movk_i32 s0, 0x4e00
	v_lshl_add_u64 v[42:43], s[48:49], 0, v[24:25]
	v_mad_i64_i32 v[24:25], s[0:1], v18, s0, v[20:21]
	v_or_b32_e32 v24, v24, v0
	s_movk_i32 s0, 0x5000
	v_lshlrev_b32_e32 v107, 16, v45
	v_lshlrev_b32_e32 v108, 16, v44
	v_lshl_add_u64 v[44:45], s[48:49], 0, v[24:25]
	v_mad_i64_i32 v[24:25], s[0:1], v18, s0, v[20:21]
	v_or_b32_e32 v24, v24, v0
	s_movk_i32 s0, 0x5200
	v_lshlrev_b32_e32 v75, 16, v46
	v_lshlrev_b32_e32 v110, 16, v47
	v_lshl_add_u64 v[46:47], s[48:49], 0, v[24:25]
	v_mad_i64_i32 v[24:25], s[0:1], v18, s0, v[20:21]
	v_or_b32_e32 v24, v24, v0
	s_movk_i32 s0, 0x5400
	v_lshlrev_b32_e32 v109, 16, v48
	v_lshlrev_b32_e32 v77, 16, v49
	v_lshl_add_u64 v[48:49], s[48:49], 0, v[24:25]
	v_mad_i64_i32 v[24:25], s[0:1], v18, s0, v[20:21]
	v_or_b32_e32 v24, v24, v0
	s_movk_i32 s0, 0x5600
	v_lshlrev_b32_e32 v76, 16, v51
	v_lshlrev_b32_e32 v78, 16, v50
	v_lshl_add_u64 v[50:51], s[48:49], 0, v[24:25]
	v_mad_i64_i32 v[24:25], s[0:1], v18, s0, v[20:21]
	v_or_b32_e32 v24, v24, v0
	s_movk_i32 s0, 0x5800
	v_lshlrev_b32_e32 v111, 16, v53
	v_lshlrev_b32_e32 v112, 16, v52
	v_lshl_add_u64 v[52:53], s[48:49], 0, v[24:25]
	v_mad_i64_i32 v[24:25], s[0:1], v18, s0, v[20:21]
	v_or_b32_e32 v24, v24, v0
	s_movk_i32 s0, 0x5a00
	v_lshl_add_u64 v[54:55], s[48:49], 0, v[24:25]
	v_mad_i64_i32 v[24:25], s[0:1], v18, s0, v[20:21]
	v_or_b32_e32 v24, v24, v0
	s_movk_i32 s0, 0x5c00
	v_lshl_add_u64 v[56:57], s[48:49], 0, v[24:25]
	v_mad_i64_i32 v[24:25], s[0:1], v18, s0, v[20:21]
	v_or_b32_e32 v24, v24, v0
	s_movk_i32 s0, 0x5e00
	v_lshl_add_u64 v[58:59], s[48:49], 0, v[24:25]
	v_mad_i64_i32 v[24:25], s[0:1], v18, s0, v[20:21]
	v_readlane_b32 s0, v251, 15
	v_readlane_b32 s1, v251, 16
	s_waitcnt vmcnt(2)
	v_lshlrev_b32_e32 v87, 16, v27
	v_lshlrev_b32_e32 v82, 16, v26
	v_lshl_add_u64 v[62:63], s[0:1], 0, v[22:23]
	v_lshlrev_b64 v[22:23], 13, v[18:19]
	v_lshl_add_u64 v[20:21], v[22:23], 0, v[20:21]
	s_waitcnt vmcnt(0)
	v_lshlrev_b32_e32 v83, 16, v29
	v_or_b32_e32 v24, v24, v0
	v_or_b32_e32 v20, v20, v0
	v_lshlrev_b32_e32 v80, 16, v17
	v_lshl_add_u64 v[60:61], s[48:49], 0, v[24:25]
	v_lshl_add_u64 v[66:67], s[92:93], 0, v[20:21]
	v_mov_b32_e32 v17, v16
	v_mov_b64_e32 v[84:85], v[82:83]
	v_mov_b32_e32 v0, v87
	v_and_b32_e32 v3, 31, v181
	v_lshlrev_b32_e32 v3, 3, v3
	v_add_u32_e32 v7, 4, v3
	ds_bpermute_b32 v16, v3, v10
	ds_bpermute_b32 v17, v7, v10
	ds_bpermute_b32 v18, v3, v12
	ds_bpermute_b32 v19, v7, v12
	v_and_b32_e32 v14, 63, v181
	v_lshlrev_b32_e32 v14, 2, v14
	v_mov_b32_e32 v20, 0
	v_mov_b32_e32 v21, 0
	v_mov_b32_e32 v22, 0
	v_mov_b32_e32 v23, 0
	v_readfirstlane_b32 s0, v97
	s_and_b32 s1, s0, 63
	s_bfe_u32 s6, s0, 0x10006
	s_lshr_b32 s7, s0, 7
	s_lshl_b32 s14, s7, 9
	s_lshr_b32 s15, s7, 2
	s_movk_i32 s22, 0x200
	s_lshl_b32 s15, s22, s15
	s_sub_u32 s22, s15, 1
	s_mul_i32 s22, s22, s6
	s_add_u32 s14, s14, s22
	s_mulk_i32 s1, 0xc00
	s_add_u32 s1, s1, s14
	s_lshl_b32 s23, s6, 8
	s_lshl_b32 s22, s1, 9
	s_add_u32 s22, s22, s23
	s_add_u32 s22, s22, 0x8e00000
	v_readlane_b32 s26, v250, 3
	v_readlane_b32 s27, v250, 4
	s_add_u32 s26, s26, s22
	s_addc_u32 s27, s27, 0
	s_lshl_b32 s22, s1, 10
	s_add_u32 s22, s22, s23
	s_add_u32 s22, s22, 0x200
	v_readlane_b32 s8, v251, 63
	v_readlane_b32 s9, v250, 0
	s_add_u32 s8, s8, s22
	s_addc_u32 s9, s9, 0
	s_lshr_b32 s15, s15, 5
	s_mov_b32 s0, -1
	s_mov_b32 s1, 0
	s_waitcnt lgkmcnt(0)
	s_cmp_eq_u32 s6, 0
	s_cbranch_scc0 .Lscan_bwd
	s_mov_b32 s22, s26
	s_mov_b32 s23, s27
	s_add_u32 s8, s8, 0x1000
	s_addc_u32 s9, s9, 0
	global_load_dword v40, v14, s[22:23] offset:0
	global_load_dword v41, v14, s[22:23] offset:512
	global_load_dword v42, v14, s[22:23] offset:1024
	global_load_dword v43, v14, s[22:23] offset:1536
	global_load_dword v44, v14, s[22:23] offset:2048
	global_load_dword v45, v14, s[22:23] offset:2560
	global_load_dword v46, v14, s[22:23] offset:3072
	global_load_dword v47, v14, s[22:23] offset:3584
	s_add_u32 s22, s22, 0x1000
	s_addc_u32 s23, s23, 0
	global_load_dword v48, v14, s[22:23] offset:0
	global_load_dword v49, v14, s[22:23] offset:512
	global_load_dword v50, v14, s[22:23] offset:1024
	global_load_dword v51, v14, s[22:23] offset:1536
	global_load_dword v52, v14, s[22:23] offset:2048
	global_load_dword v53, v14, s[22:23] offset:2560
	global_load_dword v54, v14, s[22:23] offset:3072
	global_load_dword v55, v14, s[22:23] offset:3584
	s_add_u32 s22, s22, 0x1000
	s_addc_u32 s23, s23, 0
	global_load_dword v56, v14, s[22:23] offset:0
	global_load_dword v57, v14, s[22:23] offset:512
	global_load_dword v58, v14, s[22:23] offset:1024
	global_load_dword v59, v14, s[22:23] offset:1536
	global_load_dword v60, v14, s[22:23] offset:2048
	global_load_dword v61, v14, s[22:23] offset:2560
	global_load_dword v62, v14, s[22:23] offset:3072
	global_load_dword v63, v14, s[22:23] offset:3584
	s_add_u32 s22, s22, 0x1000
	s_addc_u32 s23, s23, 0
	s_waitcnt vmcnt(0)
; #define SCAN_LOAD(buf, b) do { _Pragma("unroll") for (int k = 0; k < 16; ++k) { sr[buf][k] = __uint_as_float((unsigned)Sp[((b) + k) * sS] << 16); si[buf][k] = __uint_as_float((unsigned)Sp[((b) + k) * sS + 64] << 16); } } while (0)
; #define SCAN_STEP(buf, b) do { _Pragma("unroll") for (int k = 0; k < 16; ++k) { Ap[((b) + k) * sA] = f2bf(hr); Ap[((b) + k) * sA + 64] = f2bf(hi); \
;             const float nr = ar * hr - ai * hi + sr[buf][k], ni = ar * hi + ai * hr + si[buf][k]; hr = nr; hi = ni; } } while (0)
; __device__ __forceinline__ void scan_merge_phase(const Params& p, int G) {
;     ...
;         SCAN_LOAD(0, 0);
;         for (int b = 0; b < len; b += 32) {
;             SCAN_LOAD(1, b + 16);
;             SCAN_STEP(0, b);
;             if (b + 32 < len) SCAN_LOAD(0, b + 32);
;             SCAN_STEP(1, b + 16);
;         }
.Lscan_loop_f:
	global_load_dword v64, v14, s[22:23] offset:0
	global_load_dword v65, v14, s[22:23] offset:512
	global_load_dword v66, v14, s[22:23] offset:1024
	global_load_dword v67, v14, s[22:23] offset:1536
	global_load_dword v68, v14, s[22:23] offset:2048
	global_load_dword v69, v14, s[22:23] offset:2560
	global_load_dword v70, v14, s[22:23] offset:3072
	global_load_dword v71, v14, s[22:23] offset:3584
	s_add_u32 s22, s22, 0x1000
	s_addc_u32 s23, s23, 0
	s_waitcnt vmcnt(55)
	v_mov_b32_e32 v33, v40
	v_cvt_pk_bf16_f32 v30, v20, v21
	v_cvt_pk_bf16_f32 v31, v22, v23
	v_permlane32_swap_b32_e32 v40, v33
	v_cndmask_b32_e64 v32, v31, v30, s[0:1]
	global_store_dword v14, v32, s[8:9] offset:-4096
	v_lshlrev_b32_e32 v26, 16, v40
	v_and_b32_e32 v27, 0xffff0000, v40
	v_lshlrev_b32_e32 v28, 16, v33
	v_and_b32_e32 v29, 0xffff0000, v33
	v_pk_fma_f32 v[24:25], v[18:19], v[22:23], v[26:27] neg_lo:[1,0,0] neg_hi:[1,0,0]
	v_pk_fma_f32 v[34:35], v[18:19], v[20:21], v[28:29]
	v_pk_fma_f32 v[20:21], v[16:17], v[20:21], v[24:25]
	v_pk_fma_f32 v[22:23], v[16:17], v[22:23], v[34:35]
	s_waitcnt vmcnt(55)
	v_mov_b32_e32 v33, v41
	v_cvt_pk_bf16_f32 v30, v20, v21
	v_cvt_pk_bf16_f32 v31, v22, v23
	v_permlane32_swap_b32_e32 v41, v33
	v_cndmask_b32_e64 v32, v31, v30, s[0:1]
	global_store_dword v14, v32, s[8:9] offset:-3072
	v_lshlrev_b32_e32 v26, 16, v41
	v_and_b32_e32 v27, 0xffff0000, v41
	v_lshlrev_b32_e32 v28, 16, v33
	v_and_b32_e32 v29, 0xffff0000, v33
	v_pk_fma_f32 v[24:25], v[18:19], v[22:23], v[26:27] neg_lo:[1,0,0] neg_hi:[1,0,0]
	v_pk_fma_f32 v[34:35], v[18:19], v[20:21], v[28:29]
	v_pk_fma_f32 v[20:21], v[16:17], v[20:21], v[24:25]
	v_pk_fma_f32 v[22:23], v[16:17], v[22:23], v[34:35]
	s_waitcnt vmcnt(55)
	v_mov_b32_e32 v33, v42
	v_cvt_pk_bf16_f32 v30, v20, v21
	v_cvt_pk_bf16_f32 v31, v22, v23
	v_permlane32_swap_b32_e32 v42, v33
	v_cndmask_b32_e64 v32, v31, v30, s[0:1]
	global_store_dword v14, v32, s[8:9] offset:-2048
	v_lshlrev_b32_e32 v26, 16, v42
	v_and_b32_e32 v27, 0xffff0000, v42
	v_lshlrev_b32_e32 v28, 16, v33
	v_and_b32_e32 v29, 0xffff0000, v33
	v_pk_fma_f32 v[24:25], v[18:19], v[22:23], v[26:27] neg_lo:[1,0,0] neg_hi:[1,0,0]
	v_pk_fma_f32 v[34:35], v[18:19], v[20:21], v[28:29]
	v_pk_fma_f32 v[20:21], v[16:17], v[20:21], v[24:25]
	v_pk_fma_f32 v[22:23], v[16:17], v[22:23], v[34:35]
	s_waitcnt vmcnt(55)
	v_mov_b32_e32 v33, v43
	v_cvt_pk_bf16_f32 v30, v20, v21
	v_cvt_pk_bf16_f32 v31, v22, v23
	v_permlane32_swap_b32_e32 v43, v33
	v_cndmask_b32_e64 v32, v31, v30, s[0:1]
	global_store_dword v14, v32, s[8:9] offset:-1024
	v_lshlrev_b32_e32 v26, 16, v43
	v_and_b32_e32 v27, 0xffff0000, v43
	v_lshlrev_b32_e32 v28, 16, v33
	v_and_b32_e32 v29, 0xffff0000, v33
	v_pk_fma_f32 v[24:25], v[18:19], v[22:23], v[26:27] neg_lo:[1,0,0] neg_hi:[1,0,0]
	v_pk_fma_f32 v[34:35], v[18:19], v[20:21], v[28:29]
	v_pk_fma_f32 v[20:21], v[16:17], v[20:21], v[24:25]
	v_pk_fma_f32 v[22:23], v[16:17], v[22:23], v[34:35]
	s_waitcnt vmcnt(55)
	v_mov_b32_e32 v33, v44
	v_cvt_pk_bf16_f32 v30, v20, v21
	v_cvt_pk_bf16_f32 v31, v22, v23
	v_permlane32_swap_b32_e32 v44, v33
	v_cndmask_b32_e64 v32, v31, v30, s[0:1]
	global_store_dword v14, v32, s[8:9] offset:0
	v_lshlrev_b32_e32 v26, 16, v44
	v_and_b32_e32 v27, 0xffff0000, v44
	v_lshlrev_b32_e32 v28, 16, v33
	v_and_b32_e32 v29, 0xffff0000, v33
	v_pk_fma_f32 v[24:25], v[18:19], v[22:23], v[26:27] neg_lo:[1,0,0] neg_hi:[1,0,0]
	v_pk_fma_f32 v[34:35], v[18:19], v[20:21], v[28:29]
	v_pk_fma_f32 v[20:21], v[16:17], v[20:21], v[24:25]
	v_pk_fma_f32 v[22:23], v[16:17], v[22:23], v[34:35]
	s_waitcnt vmcnt(55)
	v_mov_b32_e32 v33, v45
	v_cvt_pk_bf16_f32 v30, v20, v21
	v_cvt_pk_bf16_f32 v31, v22, v23
	v_permlane32_swap_b32_e32 v45, v33
	v_cndmask_b32_e64 v32, v31, v30, s[0:1]
	global_store_dword v14, v32, s[8:9] offset:1024
	v_lshlrev_b32_e32 v26, 16, v45
	v_and_b32_e32 v27, 0xffff0000, v45
	v_lshlrev_b32_e32 v28, 16, v33
	v_and_b32_e32 v29, 0xffff0000, v33
	v_pk_fma_f32 v[24:25], v[18:19], v[22:23], v[26:27] neg_lo:[1,0,0] neg_hi:[1,0,0]
	v_pk_fma_f32 v[34:35], v[18:19], v[20:21], v[28:29]
	v_pk_fma_f32 v[20:21], v[16:17], v[20:21], v[24:25]
	v_pk_fma_f32 v[22:23], v[16:17], v[22:23], v[34:35]
	s_waitcnt vmcnt(55)
	v_mov_b32_e32 v33, v46
	v_cvt_pk_bf16_f32 v30, v20, v21
	v_cvt_pk_bf16_f32 v31, v22, v23
	v_permlane32_swap_b32_e32 v46, v33
	v_cndmask_b32_e64 v32, v31, v30, s[0:1]
	global_store_dword v14, v32, s[8:9] offset:2048
	v_lshlrev_b32_e32 v26, 16, v46
	v_and_b32_e32 v27, 0xffff0000, v46
	v_lshlrev_b32_e32 v28, 16, v33
	v_and_b32_e32 v29, 0xffff0000, v33
	v_pk_fma_f32 v[24:25], v[18:19], v[22:23], v[26:27] neg_lo:[1,0,0] neg_hi:[1,0,0]
	v_pk_fma_f32 v[34:35], v[18:19], v[20:21], v[28:29]
	v_pk_fma_f32 v[20:21], v[16:17], v[20:21], v[24:25]
	v_pk_fma_f32 v[22:23], v[16:17], v[22:23], v[34:35]
	s_waitcnt vmcnt(55)
	v_mov_b32_e32 v33, v47
	v_cvt_pk_bf16_f32 v30, v20, v21
	v_cvt_pk_bf16_f32 v31, v22, v23
	v_permlane32_swap_b32_e32 v47, v33
	v_cndmask_b32_e64 v32, v31, v30, s[0:1]
	global_store_dword v14, v32, s[8:9] offset:3072
	v_lshlrev_b32_e32 v26, 16, v47
	v_and_b32_e32 v27, 0xffff0000, v47
	v_lshlrev_b32_e32 v28, 16, v33
	v_and_b32_e32 v29, 0xffff0000, v33
	v_pk_fma_f32 v[24:25], v[18:19], v[22:23], v[26:27] neg_lo:[1,0,0] neg_hi:[1,0,0]
	v_pk_fma_f32 v[34:35], v[18:19], v[20:21], v[28:29]
	v_pk_fma_f32 v[20:21], v[16:17], v[20:21], v[24:25]
	v_pk_fma_f32 v[22:23], v[16:17], v[22:23], v[34:35]
	s_add_u32 s8, s8, 0x2000
	s_addc_u32 s9, s9, 0
	global_load_dword v40, v14, s[22:23] offset:0
	global_load_dword v41, v14, s[22:23] offset:512
	global_load_dword v42, v14, s[22:23] offset:1024
	global_load_dword v43, v14, s[22:23] offset:1536
	global_load_dword v44, v14, s[22:23] offset:2048
	global_load_dword v45, v14, s[22:23] offset:2560
	global_load_dword v46, v14, s[22:23] offset:3072
	global_load_dword v47, v14, s[22:23] offset:3584
	s_add_u32 s22, s22, 0x1000
	s_addc_u32 s23, s23, 0
	s_waitcnt vmcnt(55)
; #define SCAN_LOAD(buf, b) do { _Pragma("unroll") for (int k = 0; k < 16; ++k) { sr[buf][k] = __uint_as_float((unsigned)Sp[((b) + k) * sS] << 16); si[buf][k] = __uint_as_float((unsigned)Sp[((b) + k) * sS + 64] << 16); } } while (0)
; #define SCAN_STEP(buf, b) do { _Pragma("unroll") for (int k = 0; k < 16; ++k) { Ap[((b) + k) * sA] = f2bf(hr); Ap[((b) + k) * sA + 64] = f2bf(hi); \
;             const float nr = ar * hr - ai * hi + sr[buf][k], ni = ar * hi + ai * hr + si[buf][k]; hr = nr; hi = ni; } } while (0)
; __device__ __forceinline__ void scan_merge_phase(const Params& p, int G) {
;     ...
;         SCAN_LOAD(0, 0);
;         for (int b = 0; b < len; b += 32) {
;             SCAN_LOAD(1, b + 16);
;             SCAN_STEP(0, b);
;             if (b + 32 < len) SCAN_LOAD(0, b + 32);
;             SCAN_STEP(1, b + 16);
;         }
	v_mov_b32_e32 v33, v48
	v_cvt_pk_bf16_f32 v30, v20, v21
	v_cvt_pk_bf16_f32 v31, v22, v23
	v_permlane32_swap_b32_e32 v48, v33
	v_cndmask_b32_e64 v32, v31, v30, s[0:1]
	global_store_dword v14, v32, s[8:9] offset:-4096
	v_lshlrev_b32_e32 v26, 16, v48
	v_and_b32_e32 v27, 0xffff0000, v48
	v_lshlrev_b32_e32 v28, 16, v33
	v_and_b32_e32 v29, 0xffff0000, v33
	v_pk_fma_f32 v[24:25], v[18:19], v[22:23], v[26:27] neg_lo:[1,0,0] neg_hi:[1,0,0]
	v_pk_fma_f32 v[34:35], v[18:19], v[20:21], v[28:29]
	v_pk_fma_f32 v[20:21], v[16:17], v[20:21], v[24:25]
	v_pk_fma_f32 v[22:23], v[16:17], v[22:23], v[34:35]
	s_waitcnt vmcnt(55)
	v_mov_b32_e32 v33, v49
	v_cvt_pk_bf16_f32 v30, v20, v21
	v_cvt_pk_bf16_f32 v31, v22, v23
	v_permlane32_swap_b32_e32 v49, v33
	v_cndmask_b32_e64 v32, v31, v30, s[0:1]
	global_store_dword v14, v32, s[8:9] offset:-3072
	v_lshlrev_b32_e32 v26, 16, v49
	v_and_b32_e32 v27, 0xffff0000, v49
	v_lshlrev_b32_e32 v28, 16, v33
	v_and_b32_e32 v29, 0xffff0000, v33
	v_pk_fma_f32 v[24:25], v[18:19], v[22:23], v[26:27] neg_lo:[1,0,0] neg_hi:[1,0,0]
	v_pk_fma_f32 v[34:35], v[18:19], v[20:21], v[28:29]
	v_pk_fma_f32 v[20:21], v[16:17], v[20:21], v[24:25]
	v_pk_fma_f32 v[22:23], v[16:17], v[22:23], v[34:35]
	s_waitcnt vmcnt(55)
	v_mov_b32_e32 v33, v50
	v_cvt_pk_bf16_f32 v30, v20, v21
	v_cvt_pk_bf16_f32 v31, v22, v23
	v_permlane32_swap_b32_e32 v50, v33
	v_cndmask_b32_e64 v32, v31, v30, s[0:1]
	global_store_dword v14, v32, s[8:9] offset:-2048
	v_lshlrev_b32_e32 v26, 16, v50
	v_and_b32_e32 v27, 0xffff0000, v50
	v_lshlrev_b32_e32 v28, 16, v33
	v_and_b32_e32 v29, 0xffff0000, v33
	v_pk_fma_f32 v[24:25], v[18:19], v[22:23], v[26:27] neg_lo:[1,0,0] neg_hi:[1,0,0]
	v_pk_fma_f32 v[34:35], v[18:19], v[20:21], v[28:29]
	v_pk_fma_f32 v[20:21], v[16:17], v[20:21], v[24:25]
	v_pk_fma_f32 v[22:23], v[16:17], v[22:23], v[34:35]
	s_waitcnt vmcnt(55)
	v_mov_b32_e32 v33, v51
	v_cvt_pk_bf16_f32 v30, v20, v21
	v_cvt_pk_bf16_f32 v31, v22, v23
	v_permlane32_swap_b32_e32 v51, v33
	v_cndmask_b32_e64 v32, v31, v30, s[0:1]
	global_store_dword v14, v32, s[8:9] offset:-1024
	v_lshlrev_b32_e32 v26, 16, v51
	v_and_b32_e32 v27, 0xffff0000, v51
	v_lshlrev_b32_e32 v28, 16, v33
	v_and_b32_e32 v29, 0xffff0000, v33
	v_pk_fma_f32 v[24:25], v[18:19], v[22:23], v[26:27] neg_lo:[1,0,0] neg_hi:[1,0,0]
	v_pk_fma_f32 v[34:35], v[18:19], v[20:21], v[28:29]
	v_pk_fma_f32 v[20:21], v[16:17], v[20:21], v[24:25]
	v_pk_fma_f32 v[22:23], v[16:17], v[22:23], v[34:35]
	s_waitcnt vmcnt(55)
	v_mov_b32_e32 v33, v52
	v_cvt_pk_bf16_f32 v30, v20, v21
	v_cvt_pk_bf16_f32 v31, v22, v23
	v_permlane32_swap_b32_e32 v52, v33
	v_cndmask_b32_e64 v32, v31, v30, s[0:1]
	global_store_dword v14, v32, s[8:9] offset:0
	v_lshlrev_b32_e32 v26, 16, v52
	v_and_b32_e32 v27, 0xffff0000, v52
	v_lshlrev_b32_e32 v28, 16, v33
	v_and_b32_e32 v29, 0xffff0000, v33
	v_pk_fma_f32 v[24:25], v[18:19], v[22:23], v[26:27] neg_lo:[1,0,0] neg_hi:[1,0,0]
	v_pk_fma_f32 v[34:35], v[18:19], v[20:21], v[28:29]
	v_pk_fma_f32 v[20:21], v[16:17], v[20:21], v[24:25]
	v_pk_fma_f32 v[22:23], v[16:17], v[22:23], v[34:35]
	s_waitcnt vmcnt(55)
	v_mov_b32_e32 v33, v53
	v_cvt_pk_bf16_f32 v30, v20, v21
	v_cvt_pk_bf16_f32 v31, v22, v23
	v_permlane32_swap_b32_e32 v53, v33
	v_cndmask_b32_e64 v32, v31, v30, s[0:1]
	global_store_dword v14, v32, s[8:9] offset:1024
	v_lshlrev_b32_e32 v26, 16, v53
	v_and_b32_e32 v27, 0xffff0000, v53
	v_lshlrev_b32_e32 v28, 16, v33
	v_and_b32_e32 v29, 0xffff0000, v33
	v_pk_fma_f32 v[24:25], v[18:19], v[22:23], v[26:27] neg_lo:[1,0,0] neg_hi:[1,0,0]
	v_pk_fma_f32 v[34:35], v[18:19], v[20:21], v[28:29]
	v_pk_fma_f32 v[20:21], v[16:17], v[20:21], v[24:25]
	v_pk_fma_f32 v[22:23], v[16:17], v[22:23], v[34:35]
	s_waitcnt vmcnt(55)
	v_mov_b32_e32 v33, v54
	v_cvt_pk_bf16_f32 v30, v20, v21
	v_cvt_pk_bf16_f32 v31, v22, v23
	v_permlane32_swap_b32_e32 v54, v33
	v_cndmask_b32_e64 v32, v31, v30, s[0:1]
	global_store_dword v14, v32, s[8:9] offset:2048
	v_lshlrev_b32_e32 v26, 16, v54
	v_and_b32_e32 v27, 0xffff0000, v54
	v_lshlrev_b32_e32 v28, 16, v33
	v_and_b32_e32 v29, 0xffff0000, v33
	v_pk_fma_f32 v[24:25], v[18:19], v[22:23], v[26:27] neg_lo:[1,0,0] neg_hi:[1,0,0]
	v_pk_fma_f32 v[34:35], v[18:19], v[20:21], v[28:29]
	v_pk_fma_f32 v[20:21], v[16:17], v[20:21], v[24:25]
	v_pk_fma_f32 v[22:23], v[16:17], v[22:23], v[34:35]
	s_waitcnt vmcnt(55)
	v_mov_b32_e32 v33, v55
	v_cvt_pk_bf16_f32 v30, v20, v21
	v_cvt_pk_bf16_f32 v31, v22, v23
	v_permlane32_swap_b32_e32 v55, v33
	v_cndmask_b32_e64 v32, v31, v30, s[0:1]
	global_store_dword v14, v32, s[8:9] offset:3072
	v_lshlrev_b32_e32 v26, 16, v55
	v_and_b32_e32 v27, 0xffff0000, v55
	v_lshlrev_b32_e32 v28, 16, v33
	v_and_b32_e32 v29, 0xffff0000, v33
	v_pk_fma_f32 v[24:25], v[18:19], v[22:23], v[26:27] neg_lo:[1,0,0] neg_hi:[1,0,0]
	v_pk_fma_f32 v[34:35], v[18:19], v[20:21], v[28:29]
	v_pk_fma_f32 v[20:21], v[16:17], v[20:21], v[24:25]
	v_pk_fma_f32 v[22:23], v[16:17], v[22:23], v[34:35]
	s_add_u32 s8, s8, 0x2000
	s_addc_u32 s9, s9, 0
	global_load_dword v48, v14, s[22:23] offset:0
	global_load_dword v49, v14, s[22:23] offset:512
	global_load_dword v50, v14, s[22:23] offset:1024
	global_load_dword v51, v14, s[22:23] offset:1536
	global_load_dword v52, v14, s[22:23] offset:2048
	global_load_dword v53, v14, s[22:23] offset:2560
	global_load_dword v54, v14, s[22:23] offset:3072
	global_load_dword v55, v14, s[22:23] offset:3584
	s_add_u32 s22, s22, 0x1000
	s_addc_u32 s23, s23, 0
	s_waitcnt vmcnt(55)
; #define SCAN_LOAD(buf, b) do { _Pragma("unroll") for (int k = 0; k < 16; ++k) { sr[buf][k] = __uint_as_float((unsigned)Sp[((b) + k) * sS] << 16); si[buf][k] = __uint_as_float((unsigned)Sp[((b) + k) * sS + 64] << 16); } } while (0)
; #define SCAN_STEP(buf, b) do { _Pragma("unroll") for (int k = 0; k < 16; ++k) { Ap[((b) + k) * sA] = f2bf(hr); Ap[((b) + k) * sA + 64] = f2bf(hi); \
;             const float nr = ar * hr - ai * hi + sr[buf][k], ni = ar * hi + ai * hr + si[buf][k]; hr = nr; hi = ni; } } while (0)
; __device__ __forceinline__ void scan_merge_phase(const Params& p, int G) {
;     ...
;         SCAN_LOAD(0, 0);
;         for (int b = 0; b < len; b += 32) {
;             SCAN_LOAD(1, b + 16);
;             SCAN_STEP(0, b);
;             if (b + 32 < len) SCAN_LOAD(0, b + 32);
;             SCAN_STEP(1, b + 16);
;         }
	v_mov_b32_e32 v33, v56
	v_cvt_pk_bf16_f32 v30, v20, v21
	v_cvt_pk_bf16_f32 v31, v22, v23
	v_permlane32_swap_b32_e32 v56, v33
	v_cndmask_b32_e64 v32, v31, v30, s[0:1]
	global_store_dword v14, v32, s[8:9] offset:-4096
	v_lshlrev_b32_e32 v26, 16, v56
	v_and_b32_e32 v27, 0xffff0000, v56
	v_lshlrev_b32_e32 v28, 16, v33
	v_and_b32_e32 v29, 0xffff0000, v33
	v_pk_fma_f32 v[24:25], v[18:19], v[22:23], v[26:27] neg_lo:[1,0,0] neg_hi:[1,0,0]
	v_pk_fma_f32 v[34:35], v[18:19], v[20:21], v[28:29]
	v_pk_fma_f32 v[20:21], v[16:17], v[20:21], v[24:25]
	v_pk_fma_f32 v[22:23], v[16:17], v[22:23], v[34:35]
	s_waitcnt vmcnt(55)
	v_mov_b32_e32 v33, v57
	v_cvt_pk_bf16_f32 v30, v20, v21
	v_cvt_pk_bf16_f32 v31, v22, v23
	v_permlane32_swap_b32_e32 v57, v33
	v_cndmask_b32_e64 v32, v31, v30, s[0:1]
	global_store_dword v14, v32, s[8:9] offset:-3072
	v_lshlrev_b32_e32 v26, 16, v57
	v_and_b32_e32 v27, 0xffff0000, v57
	v_lshlrev_b32_e32 v28, 16, v33
	v_and_b32_e32 v29, 0xffff0000, v33
	v_pk_fma_f32 v[24:25], v[18:19], v[22:23], v[26:27] neg_lo:[1,0,0] neg_hi:[1,0,0]
	v_pk_fma_f32 v[34:35], v[18:19], v[20:21], v[28:29]
	v_pk_fma_f32 v[20:21], v[16:17], v[20:21], v[24:25]
	v_pk_fma_f32 v[22:23], v[16:17], v[22:23], v[34:35]
	s_waitcnt vmcnt(55)
	v_mov_b32_e32 v33, v58
	v_cvt_pk_bf16_f32 v30, v20, v21
	v_cvt_pk_bf16_f32 v31, v22, v23
	v_permlane32_swap_b32_e32 v58, v33
	v_cndmask_b32_e64 v32, v31, v30, s[0:1]
	global_store_dword v14, v32, s[8:9] offset:-2048
	v_lshlrev_b32_e32 v26, 16, v58
	v_and_b32_e32 v27, 0xffff0000, v58
	v_lshlrev_b32_e32 v28, 16, v33
	v_and_b32_e32 v29, 0xffff0000, v33
	v_pk_fma_f32 v[24:25], v[18:19], v[22:23], v[26:27] neg_lo:[1,0,0] neg_hi:[1,0,0]
	v_pk_fma_f32 v[34:35], v[18:19], v[20:21], v[28:29]
	v_pk_fma_f32 v[20:21], v[16:17], v[20:21], v[24:25]
	v_pk_fma_f32 v[22:23], v[16:17], v[22:23], v[34:35]
	s_waitcnt vmcnt(55)
	v_mov_b32_e32 v33, v59
	v_cvt_pk_bf16_f32 v30, v20, v21
	v_cvt_pk_bf16_f32 v31, v22, v23
	v_permlane32_swap_b32_e32 v59, v33
	v_cndmask_b32_e64 v32, v31, v30, s[0:1]
	global_store_dword v14, v32, s[8:9] offset:-1024
	v_lshlrev_b32_e32 v26, 16, v59
	v_and_b32_e32 v27, 0xffff0000, v59
	v_lshlrev_b32_e32 v28, 16, v33
	v_and_b32_e32 v29, 0xffff0000, v33
	v_pk_fma_f32 v[24:25], v[18:19], v[22:23], v[26:27] neg_lo:[1,0,0] neg_hi:[1,0,0]
	v_pk_fma_f32 v[34:35], v[18:19], v[20:21], v[28:29]
	v_pk_fma_f32 v[20:21], v[16:17], v[20:21], v[24:25]
	v_pk_fma_f32 v[22:23], v[16:17], v[22:23], v[34:35]
	s_waitcnt vmcnt(55)
	v_mov_b32_e32 v33, v60
	v_cvt_pk_bf16_f32 v30, v20, v21
	v_cvt_pk_bf16_f32 v31, v22, v23
	v_permlane32_swap_b32_e32 v60, v33
	v_cndmask_b32_e64 v32, v31, v30, s[0:1]
	global_store_dword v14, v32, s[8:9] offset:0
	v_lshlrev_b32_e32 v26, 16, v60
	v_and_b32_e32 v27, 0xffff0000, v60
	v_lshlrev_b32_e32 v28, 16, v33
	v_and_b32_e32 v29, 0xffff0000, v33
	v_pk_fma_f32 v[24:25], v[18:19], v[22:23], v[26:27] neg_lo:[1,0,0] neg_hi:[1,0,0]
	v_pk_fma_f32 v[34:35], v[18:19], v[20:21], v[28:29]
	v_pk_fma_f32 v[20:21], v[16:17], v[20:21], v[24:25]
	v_pk_fma_f32 v[22:23], v[16:17], v[22:23], v[34:35]
	s_waitcnt vmcnt(55)
	v_mov_b32_e32 v33, v61
	v_cvt_pk_bf16_f32 v30, v20, v21
	v_cvt_pk_bf16_f32 v31, v22, v23
	v_permlane32_swap_b32_e32 v61, v33
	v_cndmask_b32_e64 v32, v31, v30, s[0:1]
	global_store_dword v14, v32, s[8:9] offset:1024
	v_lshlrev_b32_e32 v26, 16, v61
	v_and_b32_e32 v27, 0xffff0000, v61
	v_lshlrev_b32_e32 v28, 16, v33
	v_and_b32_e32 v29, 0xffff0000, v33
	v_pk_fma_f32 v[24:25], v[18:19], v[22:23], v[26:27] neg_lo:[1,0,0] neg_hi:[1,0,0]
	v_pk_fma_f32 v[34:35], v[18:19], v[20:21], v[28:29]
	v_pk_fma_f32 v[20:21], v[16:17], v[20:21], v[24:25]
	v_pk_fma_f32 v[22:23], v[16:17], v[22:23], v[34:35]
	s_waitcnt vmcnt(55)
	v_mov_b32_e32 v33, v62
	v_cvt_pk_bf16_f32 v30, v20, v21
	v_cvt_pk_bf16_f32 v31, v22, v23
	v_permlane32_swap_b32_e32 v62, v33
	v_cndmask_b32_e64 v32, v31, v30, s[0:1]
	global_store_dword v14, v32, s[8:9] offset:2048
	v_lshlrev_b32_e32 v26, 16, v62
	v_and_b32_e32 v27, 0xffff0000, v62
	v_lshlrev_b32_e32 v28, 16, v33
	v_and_b32_e32 v29, 0xffff0000, v33
	v_pk_fma_f32 v[24:25], v[18:19], v[22:23], v[26:27] neg_lo:[1,0,0] neg_hi:[1,0,0]
	v_pk_fma_f32 v[34:35], v[18:19], v[20:21], v[28:29]
	v_pk_fma_f32 v[20:21], v[16:17], v[20:21], v[24:25]
	v_pk_fma_f32 v[22:23], v[16:17], v[22:23], v[34:35]
	s_waitcnt vmcnt(55)
	v_mov_b32_e32 v33, v63
	v_cvt_pk_bf16_f32 v30, v20, v21
	v_cvt_pk_bf16_f32 v31, v22, v23
	v_permlane32_swap_b32_e32 v63, v33
	v_cndmask_b32_e64 v32, v31, v30, s[0:1]
	global_store_dword v14, v32, s[8:9] offset:3072
	v_lshlrev_b32_e32 v26, 16, v63
	v_and_b32_e32 v27, 0xffff0000, v63
	v_lshlrev_b32_e32 v28, 16, v33
	v_and_b32_e32 v29, 0xffff0000, v33
	v_pk_fma_f32 v[24:25], v[18:19], v[22:23], v[26:27] neg_lo:[1,0,0] neg_hi:[1,0,0]
	v_pk_fma_f32 v[34:35], v[18:19], v[20:21], v[28:29]
	v_pk_fma_f32 v[20:21], v[16:17], v[20:21], v[24:25]
	v_pk_fma_f32 v[22:23], v[16:17], v[22:23], v[34:35]
	s_add_u32 s8, s8, 0x2000
	s_addc_u32 s9, s9, 0
	global_load_dword v56, v14, s[22:23] offset:0
	global_load_dword v57, v14, s[22:23] offset:512
	global_load_dword v58, v14, s[22:23] offset:1024
	global_load_dword v59, v14, s[22:23] offset:1536
	global_load_dword v60, v14, s[22:23] offset:2048
	global_load_dword v61, v14, s[22:23] offset:2560
	global_load_dword v62, v14, s[22:23] offset:3072
	global_load_dword v63, v14, s[22:23] offset:3584
	s_add_u32 s22, s22, 0x1000
	s_addc_u32 s23, s23, 0
	s_waitcnt vmcnt(55)
; #define SCAN_LOAD(buf, b) do { _Pragma("unroll") for (int k = 0; k < 16; ++k) { sr[buf][k] = __uint_as_float((unsigned)Sp[((b) + k) * sS] << 16); si[buf][k] = __uint_as_float((unsigned)Sp[((b) + k) * sS + 64] << 16); } } while (0)
; #define SCAN_STEP(buf, b) do { _Pragma("unroll") for (int k = 0; k < 16; ++k) { Ap[((b) + k) * sA] = f2bf(hr); Ap[((b) + k) * sA + 64] = f2bf(hi); \
;             const float nr = ar * hr - ai * hi + sr[buf][k], ni = ar * hi + ai * hr + si[buf][k]; hr = nr; hi = ni; } } while (0)
; __device__ __forceinline__ void scan_merge_phase(const Params& p, int G) {
;     ...
;         SCAN_LOAD(0, 0);
;         for (int b = 0; b < len; b += 32) {
;             SCAN_LOAD(1, b + 16);
;             SCAN_STEP(0, b);
;             if (b + 32 < len) SCAN_LOAD(0, b + 32);
;             SCAN_STEP(1, b + 16);
;         }
	v_mov_b32_e32 v33, v64
	v_cvt_pk_bf16_f32 v30, v20, v21
	v_cvt_pk_bf16_f32 v31, v22, v23
	v_permlane32_swap_b32_e32 v64, v33
	v_cndmask_b32_e64 v32, v31, v30, s[0:1]
	global_store_dword v14, v32, s[8:9] offset:-4096
	v_lshlrev_b32_e32 v26, 16, v64
	v_and_b32_e32 v27, 0xffff0000, v64
	v_lshlrev_b32_e32 v28, 16, v33
	v_and_b32_e32 v29, 0xffff0000, v33
	v_pk_fma_f32 v[24:25], v[18:19], v[22:23], v[26:27] neg_lo:[1,0,0] neg_hi:[1,0,0]
	v_pk_fma_f32 v[34:35], v[18:19], v[20:21], v[28:29]
	v_pk_fma_f32 v[20:21], v[16:17], v[20:21], v[24:25]
	v_pk_fma_f32 v[22:23], v[16:17], v[22:23], v[34:35]
	s_waitcnt vmcnt(55)
	v_mov_b32_e32 v33, v65
	v_cvt_pk_bf16_f32 v30, v20, v21
	v_cvt_pk_bf16_f32 v31, v22, v23
	v_permlane32_swap_b32_e32 v65, v33
	v_cndmask_b32_e64 v32, v31, v30, s[0:1]
	global_store_dword v14, v32, s[8:9] offset:-3072
	v_lshlrev_b32_e32 v26, 16, v65
	v_and_b32_e32 v27, 0xffff0000, v65
	v_lshlrev_b32_e32 v28, 16, v33
	v_and_b32_e32 v29, 0xffff0000, v33
	v_pk_fma_f32 v[24:25], v[18:19], v[22:23], v[26:27] neg_lo:[1,0,0] neg_hi:[1,0,0]
	v_pk_fma_f32 v[34:35], v[18:19], v[20:21], v[28:29]
	v_pk_fma_f32 v[20:21], v[16:17], v[20:21], v[24:25]
	v_pk_fma_f32 v[22:23], v[16:17], v[22:23], v[34:35]
	s_waitcnt vmcnt(55)
	v_mov_b32_e32 v33, v66
	v_cvt_pk_bf16_f32 v30, v20, v21
	v_cvt_pk_bf16_f32 v31, v22, v23
	v_permlane32_swap_b32_e32 v66, v33
	v_cndmask_b32_e64 v32, v31, v30, s[0:1]
	global_store_dword v14, v32, s[8:9] offset:-2048
	v_lshlrev_b32_e32 v26, 16, v66
	v_and_b32_e32 v27, 0xffff0000, v66
	v_lshlrev_b32_e32 v28, 16, v33
	v_and_b32_e32 v29, 0xffff0000, v33
	v_pk_fma_f32 v[24:25], v[18:19], v[22:23], v[26:27] neg_lo:[1,0,0] neg_hi:[1,0,0]
	v_pk_fma_f32 v[34:35], v[18:19], v[20:21], v[28:29]
	v_pk_fma_f32 v[20:21], v[16:17], v[20:21], v[24:25]
	v_pk_fma_f32 v[22:23], v[16:17], v[22:23], v[34:35]
	s_waitcnt vmcnt(55)
	v_mov_b32_e32 v33, v67
	v_cvt_pk_bf16_f32 v30, v20, v21
	v_cvt_pk_bf16_f32 v31, v22, v23
	v_permlane32_swap_b32_e32 v67, v33
	v_cndmask_b32_e64 v32, v31, v30, s[0:1]
	global_store_dword v14, v32, s[8:9] offset:-1024
	v_lshlrev_b32_e32 v26, 16, v67
	v_and_b32_e32 v27, 0xffff0000, v67
	v_lshlrev_b32_e32 v28, 16, v33
	v_and_b32_e32 v29, 0xffff0000, v33
	v_pk_fma_f32 v[24:25], v[18:19], v[22:23], v[26:27] neg_lo:[1,0,0] neg_hi:[1,0,0]
	v_pk_fma_f32 v[34:35], v[18:19], v[20:21], v[28:29]
	v_pk_fma_f32 v[20:21], v[16:17], v[20:21], v[24:25]
	v_pk_fma_f32 v[22:23], v[16:17], v[22:23], v[34:35]
	s_waitcnt vmcnt(55)
	v_mov_b32_e32 v33, v68
	v_cvt_pk_bf16_f32 v30, v20, v21
	v_cvt_pk_bf16_f32 v31, v22, v23
	v_permlane32_swap_b32_e32 v68, v33
	v_cndmask_b32_e64 v32, v31, v30, s[0:1]
	global_store_dword v14, v32, s[8:9] offset:0
	v_lshlrev_b32_e32 v26, 16, v68
	v_and_b32_e32 v27, 0xffff0000, v68
	v_lshlrev_b32_e32 v28, 16, v33
	v_and_b32_e32 v29, 0xffff0000, v33
	v_pk_fma_f32 v[24:25], v[18:19], v[22:23], v[26:27] neg_lo:[1,0,0] neg_hi:[1,0,0]
	v_pk_fma_f32 v[34:35], v[18:19], v[20:21], v[28:29]
	v_pk_fma_f32 v[20:21], v[16:17], v[20:21], v[24:25]
	v_pk_fma_f32 v[22:23], v[16:17], v[22:23], v[34:35]
	s_waitcnt vmcnt(55)
	v_mov_b32_e32 v33, v69
	v_cvt_pk_bf16_f32 v30, v20, v21
	v_cvt_pk_bf16_f32 v31, v22, v23
	v_permlane32_swap_b32_e32 v69, v33
	v_cndmask_b32_e64 v32, v31, v30, s[0:1]
	global_store_dword v14, v32, s[8:9] offset:1024
	v_lshlrev_b32_e32 v26, 16, v69
	v_and_b32_e32 v27, 0xffff0000, v69
	v_lshlrev_b32_e32 v28, 16, v33
	v_and_b32_e32 v29, 0xffff0000, v33
	v_pk_fma_f32 v[24:25], v[18:19], v[22:23], v[26:27] neg_lo:[1,0,0] neg_hi:[1,0,0]
	v_pk_fma_f32 v[34:35], v[18:19], v[20:21], v[28:29]
	v_pk_fma_f32 v[20:21], v[16:17], v[20:21], v[24:25]
	v_pk_fma_f32 v[22:23], v[16:17], v[22:23], v[34:35]
	s_waitcnt vmcnt(55)
	v_mov_b32_e32 v33, v70
	v_cvt_pk_bf16_f32 v30, v20, v21
	v_cvt_pk_bf16_f32 v31, v22, v23
	v_permlane32_swap_b32_e32 v70, v33
	v_cndmask_b32_e64 v32, v31, v30, s[0:1]
	global_store_dword v14, v32, s[8:9] offset:2048
	v_lshlrev_b32_e32 v26, 16, v70
	v_and_b32_e32 v27, 0xffff0000, v70
	v_lshlrev_b32_e32 v28, 16, v33
	v_and_b32_e32 v29, 0xffff0000, v33
	v_pk_fma_f32 v[24:25], v[18:19], v[22:23], v[26:27] neg_lo:[1,0,0] neg_hi:[1,0,0]
	v_pk_fma_f32 v[34:35], v[18:19], v[20:21], v[28:29]
	v_pk_fma_f32 v[20:21], v[16:17], v[20:21], v[24:25]
	v_pk_fma_f32 v[22:23], v[16:17], v[22:23], v[34:35]
	s_waitcnt vmcnt(55)
	v_mov_b32_e32 v33, v71
	v_cvt_pk_bf16_f32 v30, v20, v21
	v_cvt_pk_bf16_f32 v31, v22, v23
	v_permlane32_swap_b32_e32 v71, v33
	v_cndmask_b32_e64 v32, v31, v30, s[0:1]
	global_store_dword v14, v32, s[8:9] offset:3072
	v_lshlrev_b32_e32 v26, 16, v71
	v_and_b32_e32 v27, 0xffff0000, v71
	v_lshlrev_b32_e32 v28, 16, v33
	v_and_b32_e32 v29, 0xffff0000, v33
	v_pk_fma_f32 v[24:25], v[18:19], v[22:23], v[26:27] neg_lo:[1,0,0] neg_hi:[1,0,0]
	v_pk_fma_f32 v[34:35], v[18:19], v[20:21], v[28:29]
	v_pk_fma_f32 v[20:21], v[16:17], v[20:21], v[24:25]
	v_pk_fma_f32 v[22:23], v[16:17], v[22:23], v[34:35]
	s_add_u32 s8, s8, 0x2000
	s_addc_u32 s9, s9, 0
	s_sub_u32 s15, s15, 1
	s_cmp_lg_u32 s15, 0
	s_cbranch_scc1 .Lscan_loop_f
	s_branch .Lscan_done
; #define SCAN_LOAD(buf, b) do { _Pragma("unroll") for (int k = 0; k < 16; ++k) { sr[buf][k] = __uint_as_float((unsigned)Sp[((b) + k) * sS] << 16); si[buf][k] = __uint_as_float((unsigned)Sp[((b) + k) * sS + 64] << 16); } } while (0)
; #define SCAN_STEP(buf, b) do { _Pragma("unroll") for (int k = 0; k < 16; ++k) { Ap[((b) + k) * sA] = f2bf(hr); Ap[((b) + k) * sA + 64] = f2bf(hi); \
;             const float nr = ar * hr - ai * hi + sr[buf][k], ni = ar * hi + ai * hr + si[buf][k]; hr = nr; hi = ni; } } while (0)
; __device__ __forceinline__ void scan_merge_phase(const Params& p, int G) {
;     ...
;         const int nstart = dir == 0 ? n0 : n0 + len - 1; const long step = dir == 0 ? 1 : -1;
;         const bf16_t* Sp = S + ((size_t)g * NCHUNK + nstart) * 256 + dir * 128 + lane;
;         bf16_t* Ap = assm + ((size_t)g * NCHUNK + nstart) * 512 + 256 + dir * 128 + lane;
;         const long sS = step * 256, sA = step * 512;
;         float sr[2][16], si[2][16];
;     ...
;         SCAN_LOAD(0, 0);
;         for (int b = 0; b < len; b += 32) {
;             SCAN_LOAD(1, b + 16);
;             SCAN_STEP(0, b);
;             if (b + 32 < len) SCAN_LOAD(0, b + 32);
;             SCAN_STEP(1, b + 16);
;         }
.Lscan_bwd:
	s_sub_u32 s22, s26, 0xe00
	s_subb_u32 s23, s27, 0
	s_sub_u32 s8, s8, 0xc00
	s_subb_u32 s9, s9, 0
	global_load_dword v40, v14, s[22:23] offset:3584
	global_load_dword v41, v14, s[22:23] offset:3072
	global_load_dword v42, v14, s[22:23] offset:2560
	global_load_dword v43, v14, s[22:23] offset:2048
	global_load_dword v44, v14, s[22:23] offset:1536
	global_load_dword v45, v14, s[22:23] offset:1024
	global_load_dword v46, v14, s[22:23] offset:512
	global_load_dword v47, v14, s[22:23] offset:0
	s_sub_u32 s22, s22, 0x1000
	s_subb_u32 s23, s23, 0
	global_load_dword v48, v14, s[22:23] offset:3584
	global_load_dword v49, v14, s[22:23] offset:3072
	global_load_dword v50, v14, s[22:23] offset:2560
	global_load_dword v51, v14, s[22:23] offset:2048
	global_load_dword v52, v14, s[22:23] offset:1536
	global_load_dword v53, v14, s[22:23] offset:1024
	global_load_dword v54, v14, s[22:23] offset:512
	global_load_dword v55, v14, s[22:23] offset:0
	s_sub_u32 s22, s22, 0x1000
	s_subb_u32 s23, s23, 0
	global_load_dword v56, v14, s[22:23] offset:3584
	global_load_dword v57, v14, s[22:23] offset:3072
	global_load_dword v58, v14, s[22:23] offset:2560
	global_load_dword v59, v14, s[22:23] offset:2048
	global_load_dword v60, v14, s[22:23] offset:1536
	global_load_dword v61, v14, s[22:23] offset:1024
	global_load_dword v62, v14, s[22:23] offset:512
	global_load_dword v63, v14, s[22:23] offset:0
	s_sub_u32 s22, s22, 0x1000
	s_subb_u32 s23, s23, 0
	s_waitcnt vmcnt(0)
.Lscan_loop_b:
	global_load_dword v64, v14, s[22:23] offset:3584
	global_load_dword v65, v14, s[22:23] offset:3072
	global_load_dword v66, v14, s[22:23] offset:2560
	global_load_dword v67, v14, s[22:23] offset:2048
	global_load_dword v68, v14, s[22:23] offset:1536
	global_load_dword v69, v14, s[22:23] offset:1024
	global_load_dword v70, v14, s[22:23] offset:512
	global_load_dword v71, v14, s[22:23] offset:0
	s_sub_u32 s22, s22, 0x1000
	s_subb_u32 s23, s23, 0
	s_waitcnt vmcnt(55)
	v_mov_b32_e32 v33, v40
	v_cvt_pk_bf16_f32 v30, v20, v21
	v_cvt_pk_bf16_f32 v31, v22, v23
	v_permlane32_swap_b32_e32 v40, v33
	v_cndmask_b32_e64 v32, v31, v30, s[0:1]
	global_store_dword v14, v32, s[8:9] offset:3072
	v_lshlrev_b32_e32 v26, 16, v40
	v_and_b32_e32 v27, 0xffff0000, v40
	v_lshlrev_b32_e32 v28, 16, v33
	v_and_b32_e32 v29, 0xffff0000, v33
	v_pk_fma_f32 v[24:25], v[18:19], v[22:23], v[26:27] neg_lo:[1,0,0] neg_hi:[1,0,0]
	v_pk_fma_f32 v[34:35], v[18:19], v[20:21], v[28:29]
	v_pk_fma_f32 v[20:21], v[16:17], v[20:21], v[24:25]
	v_pk_fma_f32 v[22:23], v[16:17], v[22:23], v[34:35]
	s_waitcnt vmcnt(55)
	v_mov_b32_e32 v33, v41
	v_cvt_pk_bf16_f32 v30, v20, v21
	v_cvt_pk_bf16_f32 v31, v22, v23
	v_permlane32_swap_b32_e32 v41, v33
	v_cndmask_b32_e64 v32, v31, v30, s[0:1]
	global_store_dword v14, v32, s[8:9] offset:2048
	v_lshlrev_b32_e32 v26, 16, v41
	v_and_b32_e32 v27, 0xffff0000, v41
	v_lshlrev_b32_e32 v28, 16, v33
	v_and_b32_e32 v29, 0xffff0000, v33
	v_pk_fma_f32 v[24:25], v[18:19], v[22:23], v[26:27] neg_lo:[1,0,0] neg_hi:[1,0,0]
	v_pk_fma_f32 v[34:35], v[18:19], v[20:21], v[28:29]
	v_pk_fma_f32 v[20:21], v[16:17], v[20:21], v[24:25]
	v_pk_fma_f32 v[22:23], v[16:17], v[22:23], v[34:35]
	s_waitcnt vmcnt(55)
	v_mov_b32_e32 v33, v42
	v_cvt_pk_bf16_f32 v30, v20, v21
	v_cvt_pk_bf16_f32 v31, v22, v23
	v_permlane32_swap_b32_e32 v42, v33
	v_cndmask_b32_e64 v32, v31, v30, s[0:1]
	global_store_dword v14, v32, s[8:9] offset:1024
	v_lshlrev_b32_e32 v26, 16, v42
	v_and_b32_e32 v27, 0xffff0000, v42
	v_lshlrev_b32_e32 v28, 16, v33
	v_and_b32_e32 v29, 0xffff0000, v33
	v_pk_fma_f32 v[24:25], v[18:19], v[22:23], v[26:27] neg_lo:[1,0,0] neg_hi:[1,0,0]
	v_pk_fma_f32 v[34:35], v[18:19], v[20:21], v[28:29]
	v_pk_fma_f32 v[20:21], v[16:17], v[20:21], v[24:25]
	v_pk_fma_f32 v[22:23], v[16:17], v[22:23], v[34:35]
	s_waitcnt vmcnt(55)
	v_mov_b32_e32 v33, v43
	v_cvt_pk_bf16_f32 v30, v20, v21
	v_cvt_pk_bf16_f32 v31, v22, v23
	v_permlane32_swap_b32_e32 v43, v33
	v_cndmask_b32_e64 v32, v31, v30, s[0:1]
	global_store_dword v14, v32, s[8:9] offset:0
	v_lshlrev_b32_e32 v26, 16, v43
	v_and_b32_e32 v27, 0xffff0000, v43
	v_lshlrev_b32_e32 v28, 16, v33
	v_and_b32_e32 v29, 0xffff0000, v33
	v_pk_fma_f32 v[24:25], v[18:19], v[22:23], v[26:27] neg_lo:[1,0,0] neg_hi:[1,0,0]
	v_pk_fma_f32 v[34:35], v[18:19], v[20:21], v[28:29]
	v_pk_fma_f32 v[20:21], v[16:17], v[20:21], v[24:25]
	v_pk_fma_f32 v[22:23], v[16:17], v[22:23], v[34:35]
	s_waitcnt vmcnt(55)
	v_mov_b32_e32 v33, v44
	v_cvt_pk_bf16_f32 v30, v20, v21
	v_cvt_pk_bf16_f32 v31, v22, v23
	v_permlane32_swap_b32_e32 v44, v33
	v_cndmask_b32_e64 v32, v31, v30, s[0:1]
	global_store_dword v14, v32, s[8:9] offset:-1024
	v_lshlrev_b32_e32 v26, 16, v44
	v_and_b32_e32 v27, 0xffff0000, v44
	v_lshlrev_b32_e32 v28, 16, v33
	v_and_b32_e32 v29, 0xffff0000, v33
	v_pk_fma_f32 v[24:25], v[18:19], v[22:23], v[26:27] neg_lo:[1,0,0] neg_hi:[1,0,0]
	v_pk_fma_f32 v[34:35], v[18:19], v[20:21], v[28:29]
	v_pk_fma_f32 v[20:21], v[16:17], v[20:21], v[24:25]
	v_pk_fma_f32 v[22:23], v[16:17], v[22:23], v[34:35]
	s_waitcnt vmcnt(55)
	v_mov_b32_e32 v33, v45
	v_cvt_pk_bf16_f32 v30, v20, v21
	v_cvt_pk_bf16_f32 v31, v22, v23
	v_permlane32_swap_b32_e32 v45, v33
	v_cndmask_b32_e64 v32, v31, v30, s[0:1]
	global_store_dword v14, v32, s[8:9] offset:-2048
	v_lshlrev_b32_e32 v26, 16, v45
	v_and_b32_e32 v27, 0xffff0000, v45
	v_lshlrev_b32_e32 v28, 16, v33
	v_and_b32_e32 v29, 0xffff0000, v33
	v_pk_fma_f32 v[24:25], v[18:19], v[22:23], v[26:27] neg_lo:[1,0,0] neg_hi:[1,0,0]
	v_pk_fma_f32 v[34:35], v[18:19], v[20:21], v[28:29]
	v_pk_fma_f32 v[20:21], v[16:17], v[20:21], v[24:25]
	v_pk_fma_f32 v[22:23], v[16:17], v[22:23], v[34:35]
	s_waitcnt vmcnt(55)
; #define SCAN_LOAD(buf, b) do { _Pragma("unroll") for (int k = 0; k < 16; ++k) { sr[buf][k] = __uint_as_float((unsigned)Sp[((b) + k) * sS] << 16); si[buf][k] = __uint_as_float((unsigned)Sp[((b) + k) * sS + 64] << 16); } } while (0)
; #define SCAN_STEP(buf, b) do { _Pragma("unroll") for (int k = 0; k < 16; ++k) { Ap[((b) + k) * sA] = f2bf(hr); Ap[((b) + k) * sA + 64] = f2bf(hi); \
;             const float nr = ar * hr - ai * hi + sr[buf][k], ni = ar * hi + ai * hr + si[buf][k]; hr = nr; hi = ni; } } while (0)
; __device__ __forceinline__ void scan_merge_phase(const Params& p, int G) {
;     ...
;         const int nstart = dir == 0 ? n0 : n0 + len - 1; const long step = dir == 0 ? 1 : -1;
;         const bf16_t* Sp = S + ((size_t)g * NCHUNK + nstart) * 256 + dir * 128 + lane;
;         bf16_t* Ap = assm + ((size_t)g * NCHUNK + nstart) * 512 + 256 + dir * 128 + lane;
;         const long sS = step * 256, sA = step * 512;
;         float sr[2][16], si[2][16];
;     ...
;         SCAN_LOAD(0, 0);
;         for (int b = 0; b < len; b += 32) {
;             SCAN_LOAD(1, b + 16);
;             SCAN_STEP(0, b);
;             if (b + 32 < len) SCAN_LOAD(0, b + 32);
;             SCAN_STEP(1, b + 16);
;         }
	v_mov_b32_e32 v33, v46
	v_cvt_pk_bf16_f32 v30, v20, v21
	v_cvt_pk_bf16_f32 v31, v22, v23
	v_permlane32_swap_b32_e32 v46, v33
	v_cndmask_b32_e64 v32, v31, v30, s[0:1]
	global_store_dword v14, v32, s[8:9] offset:-3072
	v_lshlrev_b32_e32 v26, 16, v46
	v_and_b32_e32 v27, 0xffff0000, v46
	v_lshlrev_b32_e32 v28, 16, v33
	v_and_b32_e32 v29, 0xffff0000, v33
	v_pk_fma_f32 v[24:25], v[18:19], v[22:23], v[26:27] neg_lo:[1,0,0] neg_hi:[1,0,0]
	v_pk_fma_f32 v[34:35], v[18:19], v[20:21], v[28:29]
	v_pk_fma_f32 v[20:21], v[16:17], v[20:21], v[24:25]
	v_pk_fma_f32 v[22:23], v[16:17], v[22:23], v[34:35]
	s_waitcnt vmcnt(55)
	v_mov_b32_e32 v33, v47
	v_cvt_pk_bf16_f32 v30, v20, v21
	v_cvt_pk_bf16_f32 v31, v22, v23
	v_permlane32_swap_b32_e32 v47, v33
	v_cndmask_b32_e64 v32, v31, v30, s[0:1]
	global_store_dword v14, v32, s[8:9] offset:-4096
	v_lshlrev_b32_e32 v26, 16, v47
	v_and_b32_e32 v27, 0xffff0000, v47
	v_lshlrev_b32_e32 v28, 16, v33
	v_and_b32_e32 v29, 0xffff0000, v33
	v_pk_fma_f32 v[24:25], v[18:19], v[22:23], v[26:27] neg_lo:[1,0,0] neg_hi:[1,0,0]
	v_pk_fma_f32 v[34:35], v[18:19], v[20:21], v[28:29]
	v_pk_fma_f32 v[20:21], v[16:17], v[20:21], v[24:25]
	v_pk_fma_f32 v[22:23], v[16:17], v[22:23], v[34:35]
	s_sub_u32 s8, s8, 0x2000
	s_subb_u32 s9, s9, 0
	global_load_dword v40, v14, s[22:23] offset:3584
	global_load_dword v41, v14, s[22:23] offset:3072
	global_load_dword v42, v14, s[22:23] offset:2560
	global_load_dword v43, v14, s[22:23] offset:2048
	global_load_dword v44, v14, s[22:23] offset:1536
	global_load_dword v45, v14, s[22:23] offset:1024
	global_load_dword v46, v14, s[22:23] offset:512
	global_load_dword v47, v14, s[22:23] offset:0
	s_sub_u32 s22, s22, 0x1000
	s_subb_u32 s23, s23, 0
	s_waitcnt vmcnt(55)
	v_mov_b32_e32 v33, v48
	v_cvt_pk_bf16_f32 v30, v20, v21
	v_cvt_pk_bf16_f32 v31, v22, v23
	v_permlane32_swap_b32_e32 v48, v33
	v_cndmask_b32_e64 v32, v31, v30, s[0:1]
	global_store_dword v14, v32, s[8:9] offset:3072
	v_lshlrev_b32_e32 v26, 16, v48
	v_and_b32_e32 v27, 0xffff0000, v48
	v_lshlrev_b32_e32 v28, 16, v33
	v_and_b32_e32 v29, 0xffff0000, v33
	v_pk_fma_f32 v[24:25], v[18:19], v[22:23], v[26:27] neg_lo:[1,0,0] neg_hi:[1,0,0]
	v_pk_fma_f32 v[34:35], v[18:19], v[20:21], v[28:29]
	v_pk_fma_f32 v[20:21], v[16:17], v[20:21], v[24:25]
	v_pk_fma_f32 v[22:23], v[16:17], v[22:23], v[34:35]
	s_waitcnt vmcnt(55)
	v_mov_b32_e32 v33, v49
	v_cvt_pk_bf16_f32 v30, v20, v21
	v_cvt_pk_bf16_f32 v31, v22, v23
	v_permlane32_swap_b32_e32 v49, v33
	v_cndmask_b32_e64 v32, v31, v30, s[0:1]
	global_store_dword v14, v32, s[8:9] offset:2048
	v_lshlrev_b32_e32 v26, 16, v49
	v_and_b32_e32 v27, 0xffff0000, v49
	v_lshlrev_b32_e32 v28, 16, v33
	v_and_b32_e32 v29, 0xffff0000, v33
	v_pk_fma_f32 v[24:25], v[18:19], v[22:23], v[26:27] neg_lo:[1,0,0] neg_hi:[1,0,0]
	v_pk_fma_f32 v[34:35], v[18:19], v[20:21], v[28:29]
	v_pk_fma_f32 v[20:21], v[16:17], v[20:21], v[24:25]
	v_pk_fma_f32 v[22:23], v[16:17], v[22:23], v[34:35]
	s_waitcnt vmcnt(55)
	v_mov_b32_e32 v33, v50
	v_cvt_pk_bf16_f32 v30, v20, v21
	v_cvt_pk_bf16_f32 v31, v22, v23
	v_permlane32_swap_b32_e32 v50, v33
	v_cndmask_b32_e64 v32, v31, v30, s[0:1]
	global_store_dword v14, v32, s[8:9] offset:1024
	v_lshlrev_b32_e32 v26, 16, v50
	v_and_b32_e32 v27, 0xffff0000, v50
	v_lshlrev_b32_e32 v28, 16, v33
	v_and_b32_e32 v29, 0xffff0000, v33
	v_pk_fma_f32 v[24:25], v[18:19], v[22:23], v[26:27] neg_lo:[1,0,0] neg_hi:[1,0,0]
	v_pk_fma_f32 v[34:35], v[18:19], v[20:21], v[28:29]
	v_pk_fma_f32 v[20:21], v[16:17], v[20:21], v[24:25]
	v_pk_fma_f32 v[22:23], v[16:17], v[22:23], v[34:35]
	s_waitcnt vmcnt(55)
	v_mov_b32_e32 v33, v51
	v_cvt_pk_bf16_f32 v30, v20, v21
	v_cvt_pk_bf16_f32 v31, v22, v23
	v_permlane32_swap_b32_e32 v51, v33
	v_cndmask_b32_e64 v32, v31, v30, s[0:1]
	global_store_dword v14, v32, s[8:9] offset:0
	v_lshlrev_b32_e32 v26, 16, v51
	v_and_b32_e32 v27, 0xffff0000, v51
	v_lshlrev_b32_e32 v28, 16, v33
	v_and_b32_e32 v29, 0xffff0000, v33
	v_pk_fma_f32 v[24:25], v[18:19], v[22:23], v[26:27] neg_lo:[1,0,0] neg_hi:[1,0,0]
	v_pk_fma_f32 v[34:35], v[18:19], v[20:21], v[28:29]
	v_pk_fma_f32 v[20:21], v[16:17], v[20:21], v[24:25]
	v_pk_fma_f32 v[22:23], v[16:17], v[22:23], v[34:35]
	s_waitcnt vmcnt(55)
	v_mov_b32_e32 v33, v52
	v_cvt_pk_bf16_f32 v30, v20, v21
	v_cvt_pk_bf16_f32 v31, v22, v23
	v_permlane32_swap_b32_e32 v52, v33
	v_cndmask_b32_e64 v32, v31, v30, s[0:1]
	global_store_dword v14, v32, s[8:9] offset:-1024
	v_lshlrev_b32_e32 v26, 16, v52
	v_and_b32_e32 v27, 0xffff0000, v52
	v_lshlrev_b32_e32 v28, 16, v33
	v_and_b32_e32 v29, 0xffff0000, v33
	v_pk_fma_f32 v[24:25], v[18:19], v[22:23], v[26:27] neg_lo:[1,0,0] neg_hi:[1,0,0]
	v_pk_fma_f32 v[34:35], v[18:19], v[20:21], v[28:29]
	v_pk_fma_f32 v[20:21], v[16:17], v[20:21], v[24:25]
	v_pk_fma_f32 v[22:23], v[16:17], v[22:23], v[34:35]
	s_waitcnt vmcnt(55)
	v_mov_b32_e32 v33, v53
	v_cvt_pk_bf16_f32 v30, v20, v21
	v_cvt_pk_bf16_f32 v31, v22, v23
	v_permlane32_swap_b32_e32 v53, v33
	v_cndmask_b32_e64 v32, v31, v30, s[0:1]
	global_store_dword v14, v32, s[8:9] offset:-2048
	v_lshlrev_b32_e32 v26, 16, v53
	v_and_b32_e32 v27, 0xffff0000, v53
	v_lshlrev_b32_e32 v28, 16, v33
	v_and_b32_e32 v29, 0xffff0000, v33
	v_pk_fma_f32 v[24:25], v[18:19], v[22:23], v[26:27] neg_lo:[1,0,0] neg_hi:[1,0,0]
	v_pk_fma_f32 v[34:35], v[18:19], v[20:21], v[28:29]
	v_pk_fma_f32 v[20:21], v[16:17], v[20:21], v[24:25]
	v_pk_fma_f32 v[22:23], v[16:17], v[22:23], v[34:35]
	s_waitcnt vmcnt(55)
; #define SCAN_LOAD(buf, b) do { _Pragma("unroll") for (int k = 0; k < 16; ++k) { sr[buf][k] = __uint_as_float((unsigned)Sp[((b) + k) * sS] << 16); si[buf][k] = __uint_as_float((unsigned)Sp[((b) + k) * sS + 64] << 16); } } while (0)
; #define SCAN_STEP(buf, b) do { _Pragma("unroll") for (int k = 0; k < 16; ++k) { Ap[((b) + k) * sA] = f2bf(hr); Ap[((b) + k) * sA + 64] = f2bf(hi); \
;             const float nr = ar * hr - ai * hi + sr[buf][k], ni = ar * hi + ai * hr + si[buf][k]; hr = nr; hi = ni; } } while (0)
; __device__ __forceinline__ void scan_merge_phase(const Params& p, int G) {
;     ...
;         const int nstart = dir == 0 ? n0 : n0 + len - 1; const long step = dir == 0 ? 1 : -1;
;         const bf16_t* Sp = S + ((size_t)g * NCHUNK + nstart) * 256 + dir * 128 + lane;
;         bf16_t* Ap = assm + ((size_t)g * NCHUNK + nstart) * 512 + 256 + dir * 128 + lane;
;         const long sS = step * 256, sA = step * 512;
;         float sr[2][16], si[2][16];
;     ...
;         SCAN_LOAD(0, 0);
;         for (int b = 0; b < len; b += 32) {
;             SCAN_LOAD(1, b + 16);
;             SCAN_STEP(0, b);
;             if (b + 32 < len) SCAN_LOAD(0, b + 32);
;             SCAN_STEP(1, b + 16);
;         }
	v_mov_b32_e32 v33, v54
	v_cvt_pk_bf16_f32 v30, v20, v21
	v_cvt_pk_bf16_f32 v31, v22, v23
	v_permlane32_swap_b32_e32 v54, v33
	v_cndmask_b32_e64 v32, v31, v30, s[0:1]
	global_store_dword v14, v32, s[8:9] offset:-3072
	v_lshlrev_b32_e32 v26, 16, v54
	v_and_b32_e32 v27, 0xffff0000, v54
	v_lshlrev_b32_e32 v28, 16, v33
	v_and_b32_e32 v29, 0xffff0000, v33
	v_pk_fma_f32 v[24:25], v[18:19], v[22:23], v[26:27] neg_lo:[1,0,0] neg_hi:[1,0,0]
	v_pk_fma_f32 v[34:35], v[18:19], v[20:21], v[28:29]
	v_pk_fma_f32 v[20:21], v[16:17], v[20:21], v[24:25]
	v_pk_fma_f32 v[22:23], v[16:17], v[22:23], v[34:35]
	s_waitcnt vmcnt(55)
	v_mov_b32_e32 v33, v55
	v_cvt_pk_bf16_f32 v30, v20, v21
	v_cvt_pk_bf16_f32 v31, v22, v23
	v_permlane32_swap_b32_e32 v55, v33
	v_cndmask_b32_e64 v32, v31, v30, s[0:1]
	global_store_dword v14, v32, s[8:9] offset:-4096
	v_lshlrev_b32_e32 v26, 16, v55
	v_and_b32_e32 v27, 0xffff0000, v55
	v_lshlrev_b32_e32 v28, 16, v33
	v_and_b32_e32 v29, 0xffff0000, v33
	v_pk_fma_f32 v[24:25], v[18:19], v[22:23], v[26:27] neg_lo:[1,0,0] neg_hi:[1,0,0]
	v_pk_fma_f32 v[34:35], v[18:19], v[20:21], v[28:29]
	v_pk_fma_f32 v[20:21], v[16:17], v[20:21], v[24:25]
	v_pk_fma_f32 v[22:23], v[16:17], v[22:23], v[34:35]
	s_sub_u32 s8, s8, 0x2000
	s_subb_u32 s9, s9, 0
	global_load_dword v48, v14, s[22:23] offset:3584
	global_load_dword v49, v14, s[22:23] offset:3072
	global_load_dword v50, v14, s[22:23] offset:2560
	global_load_dword v51, v14, s[22:23] offset:2048
	global_load_dword v52, v14, s[22:23] offset:1536
	global_load_dword v53, v14, s[22:23] offset:1024
	global_load_dword v54, v14, s[22:23] offset:512
	global_load_dword v55, v14, s[22:23] offset:0
	s_sub_u32 s22, s22, 0x1000
	s_subb_u32 s23, s23, 0
	s_waitcnt vmcnt(55)
	v_mov_b32_e32 v33, v56
	v_cvt_pk_bf16_f32 v30, v20, v21
	v_cvt_pk_bf16_f32 v31, v22, v23
	v_permlane32_swap_b32_e32 v56, v33
	v_cndmask_b32_e64 v32, v31, v30, s[0:1]
	global_store_dword v14, v32, s[8:9] offset:3072
	v_lshlrev_b32_e32 v26, 16, v56
	v_and_b32_e32 v27, 0xffff0000, v56
	v_lshlrev_b32_e32 v28, 16, v33
	v_and_b32_e32 v29, 0xffff0000, v33
	v_pk_fma_f32 v[24:25], v[18:19], v[22:23], v[26:27] neg_lo:[1,0,0] neg_hi:[1,0,0]
	v_pk_fma_f32 v[34:35], v[18:19], v[20:21], v[28:29]
	v_pk_fma_f32 v[20:21], v[16:17], v[20:21], v[24:25]
	v_pk_fma_f32 v[22:23], v[16:17], v[22:23], v[34:35]
	s_waitcnt vmcnt(55)
	v_mov_b32_e32 v33, v57
	v_cvt_pk_bf16_f32 v30, v20, v21
	v_cvt_pk_bf16_f32 v31, v22, v23
	v_permlane32_swap_b32_e32 v57, v33
	v_cndmask_b32_e64 v32, v31, v30, s[0:1]
	global_store_dword v14, v32, s[8:9] offset:2048
	v_lshlrev_b32_e32 v26, 16, v57
	v_and_b32_e32 v27, 0xffff0000, v57
	v_lshlrev_b32_e32 v28, 16, v33
	v_and_b32_e32 v29, 0xffff0000, v33
	v_pk_fma_f32 v[24:25], v[18:19], v[22:23], v[26:27] neg_lo:[1,0,0] neg_hi:[1,0,0]
	v_pk_fma_f32 v[34:35], v[18:19], v[20:21], v[28:29]
	v_pk_fma_f32 v[20:21], v[16:17], v[20:21], v[24:25]
	v_pk_fma_f32 v[22:23], v[16:17], v[22:23], v[34:35]
	s_waitcnt vmcnt(55)
	v_mov_b32_e32 v33, v58
	v_cvt_pk_bf16_f32 v30, v20, v21
	v_cvt_pk_bf16_f32 v31, v22, v23
	v_permlane32_swap_b32_e32 v58, v33
	v_cndmask_b32_e64 v32, v31, v30, s[0:1]
	global_store_dword v14, v32, s[8:9] offset:1024
	v_lshlrev_b32_e32 v26, 16, v58
	v_and_b32_e32 v27, 0xffff0000, v58
	v_lshlrev_b32_e32 v28, 16, v33
	v_and_b32_e32 v29, 0xffff0000, v33
	v_pk_fma_f32 v[24:25], v[18:19], v[22:23], v[26:27] neg_lo:[1,0,0] neg_hi:[1,0,0]
	v_pk_fma_f32 v[34:35], v[18:19], v[20:21], v[28:29]
	v_pk_fma_f32 v[20:21], v[16:17], v[20:21], v[24:25]
	v_pk_fma_f32 v[22:23], v[16:17], v[22:23], v[34:35]
	s_waitcnt vmcnt(55)
	v_mov_b32_e32 v33, v59
	v_cvt_pk_bf16_f32 v30, v20, v21
	v_cvt_pk_bf16_f32 v31, v22, v23
	v_permlane32_swap_b32_e32 v59, v33
	v_cndmask_b32_e64 v32, v31, v30, s[0:1]
	global_store_dword v14, v32, s[8:9] offset:0
	v_lshlrev_b32_e32 v26, 16, v59
	v_and_b32_e32 v27, 0xffff0000, v59
	v_lshlrev_b32_e32 v28, 16, v33
	v_and_b32_e32 v29, 0xffff0000, v33
	v_pk_fma_f32 v[24:25], v[18:19], v[22:23], v[26:27] neg_lo:[1,0,0] neg_hi:[1,0,0]
	v_pk_fma_f32 v[34:35], v[18:19], v[20:21], v[28:29]
	v_pk_fma_f32 v[20:21], v[16:17], v[20:21], v[24:25]
	v_pk_fma_f32 v[22:23], v[16:17], v[22:23], v[34:35]
	s_waitcnt vmcnt(55)
	v_mov_b32_e32 v33, v60
	v_cvt_pk_bf16_f32 v30, v20, v21
	v_cvt_pk_bf16_f32 v31, v22, v23
	v_permlane32_swap_b32_e32 v60, v33
	v_cndmask_b32_e64 v32, v31, v30, s[0:1]
	global_store_dword v14, v32, s[8:9] offset:-1024
	v_lshlrev_b32_e32 v26, 16, v60
	v_and_b32_e32 v27, 0xffff0000, v60
	v_lshlrev_b32_e32 v28, 16, v33
	v_and_b32_e32 v29, 0xffff0000, v33
	v_pk_fma_f32 v[24:25], v[18:19], v[22:23], v[26:27] neg_lo:[1,0,0] neg_hi:[1,0,0]
	v_pk_fma_f32 v[34:35], v[18:19], v[20:21], v[28:29]
	v_pk_fma_f32 v[20:21], v[16:17], v[20:21], v[24:25]
	v_pk_fma_f32 v[22:23], v[16:17], v[22:23], v[34:35]
	s_waitcnt vmcnt(55)
	v_mov_b32_e32 v33, v61
	v_cvt_pk_bf16_f32 v30, v20, v21
	v_cvt_pk_bf16_f32 v31, v22, v23
	v_permlane32_swap_b32_e32 v61, v33
	v_cndmask_b32_e64 v32, v31, v30, s[0:1]
	global_store_dword v14, v32, s[8:9] offset:-2048
	v_lshlrev_b32_e32 v26, 16, v61
	v_and_b32_e32 v27, 0xffff0000, v61
	v_lshlrev_b32_e32 v28, 16, v33
	v_and_b32_e32 v29, 0xffff0000, v33
	v_pk_fma_f32 v[24:25], v[18:19], v[22:23], v[26:27] neg_lo:[1,0,0] neg_hi:[1,0,0]
	v_pk_fma_f32 v[34:35], v[18:19], v[20:21], v[28:29]
	v_pk_fma_f32 v[20:21], v[16:17], v[20:21], v[24:25]
	v_pk_fma_f32 v[22:23], v[16:17], v[22:23], v[34:35]
	s_waitcnt vmcnt(55)
; #define SCAN_LOAD(buf, b) do { _Pragma("unroll") for (int k = 0; k < 16; ++k) { sr[buf][k] = __uint_as_float((unsigned)Sp[((b) + k) * sS] << 16); si[buf][k] = __uint_as_float((unsigned)Sp[((b) + k) * sS + 64] << 16); } } while (0)
; #define SCAN_STEP(buf, b) do { _Pragma("unroll") for (int k = 0; k < 16; ++k) { Ap[((b) + k) * sA] = f2bf(hr); Ap[((b) + k) * sA + 64] = f2bf(hi); \
;             const float nr = ar * hr - ai * hi + sr[buf][k], ni = ar * hi + ai * hr + si[buf][k]; hr = nr; hi = ni; } } while (0)
; __device__ __forceinline__ void scan_merge_phase(const Params& p, int G) {
;     ...
;         const int nstart = dir == 0 ? n0 : n0 + len - 1; const long step = dir == 0 ? 1 : -1;
;         const bf16_t* Sp = S + ((size_t)g * NCHUNK + nstart) * 256 + dir * 128 + lane;
;         bf16_t* Ap = assm + ((size_t)g * NCHUNK + nstart) * 512 + 256 + dir * 128 + lane;
;         const long sS = step * 256, sA = step * 512;
;         float sr[2][16], si[2][16];
;     ...
;         SCAN_LOAD(0, 0);
;         for (int b = 0; b < len; b += 32) {
;             SCAN_LOAD(1, b + 16);
;             SCAN_STEP(0, b);
;             if (b + 32 < len) SCAN_LOAD(0, b + 32);
;             SCAN_STEP(1, b + 16);
;         }
	v_mov_b32_e32 v33, v62
	v_cvt_pk_bf16_f32 v30, v20, v21
	v_cvt_pk_bf16_f32 v31, v22, v23
	v_permlane32_swap_b32_e32 v62, v33
	v_cndmask_b32_e64 v32, v31, v30, s[0:1]
	global_store_dword v14, v32, s[8:9] offset:-3072
	v_lshlrev_b32_e32 v26, 16, v62
	v_and_b32_e32 v27, 0xffff0000, v62
	v_lshlrev_b32_e32 v28, 16, v33
	v_and_b32_e32 v29, 0xffff0000, v33
	v_pk_fma_f32 v[24:25], v[18:19], v[22:23], v[26:27] neg_lo:[1,0,0] neg_hi:[1,0,0]
	v_pk_fma_f32 v[34:35], v[18:19], v[20:21], v[28:29]
	v_pk_fma_f32 v[20:21], v[16:17], v[20:21], v[24:25]
	v_pk_fma_f32 v[22:23], v[16:17], v[22:23], v[34:35]
	s_waitcnt vmcnt(55)
	v_mov_b32_e32 v33, v63
	v_cvt_pk_bf16_f32 v30, v20, v21
	v_cvt_pk_bf16_f32 v31, v22, v23
	v_permlane32_swap_b32_e32 v63, v33
	v_cndmask_b32_e64 v32, v31, v30, s[0:1]
	global_store_dword v14, v32, s[8:9] offset:-4096
	v_lshlrev_b32_e32 v26, 16, v63
	v_and_b32_e32 v27, 0xffff0000, v63
	v_lshlrev_b32_e32 v28, 16, v33
	v_and_b32_e32 v29, 0xffff0000, v33
	v_pk_fma_f32 v[24:25], v[18:19], v[22:23], v[26:27] neg_lo:[1,0,0] neg_hi:[1,0,0]
	v_pk_fma_f32 v[34:35], v[18:19], v[20:21], v[28:29]
	v_pk_fma_f32 v[20:21], v[16:17], v[20:21], v[24:25]
	v_pk_fma_f32 v[22:23], v[16:17], v[22:23], v[34:35]
	s_sub_u32 s8, s8, 0x2000
	s_subb_u32 s9, s9, 0
	global_load_dword v56, v14, s[22:23] offset:3584
	global_load_dword v57, v14, s[22:23] offset:3072
	global_load_dword v58, v14, s[22:23] offset:2560
	global_load_dword v59, v14, s[22:23] offset:2048
	global_load_dword v60, v14, s[22:23] offset:1536
	global_load_dword v61, v14, s[22:23] offset:1024
	global_load_dword v62, v14, s[22:23] offset:512
	global_load_dword v63, v14, s[22:23] offset:0
	s_sub_u32 s22, s22, 0x1000
	s_subb_u32 s23, s23, 0
	s_waitcnt vmcnt(55)
	v_mov_b32_e32 v33, v64
	v_cvt_pk_bf16_f32 v30, v20, v21
	v_cvt_pk_bf16_f32 v31, v22, v23
	v_permlane32_swap_b32_e32 v64, v33
	v_cndmask_b32_e64 v32, v31, v30, s[0:1]
	global_store_dword v14, v32, s[8:9] offset:3072
	v_lshlrev_b32_e32 v26, 16, v64
	v_and_b32_e32 v27, 0xffff0000, v64
	v_lshlrev_b32_e32 v28, 16, v33
	v_and_b32_e32 v29, 0xffff0000, v33
	v_pk_fma_f32 v[24:25], v[18:19], v[22:23], v[26:27] neg_lo:[1,0,0] neg_hi:[1,0,0]
	v_pk_fma_f32 v[34:35], v[18:19], v[20:21], v[28:29]
	v_pk_fma_f32 v[20:21], v[16:17], v[20:21], v[24:25]
	v_pk_fma_f32 v[22:23], v[16:17], v[22:23], v[34:35]
	s_waitcnt vmcnt(55)
	v_mov_b32_e32 v33, v65
	v_cvt_pk_bf16_f32 v30, v20, v21
	v_cvt_pk_bf16_f32 v31, v22, v23
	v_permlane32_swap_b32_e32 v65, v33
	v_cndmask_b32_e64 v32, v31, v30, s[0:1]
	global_store_dword v14, v32, s[8:9] offset:2048
	v_lshlrev_b32_e32 v26, 16, v65
	v_and_b32_e32 v27, 0xffff0000, v65
	v_lshlrev_b32_e32 v28, 16, v33
	v_and_b32_e32 v29, 0xffff0000, v33
	v_pk_fma_f32 v[24:25], v[18:19], v[22:23], v[26:27] neg_lo:[1,0,0] neg_hi:[1,0,0]
	v_pk_fma_f32 v[34:35], v[18:19], v[20:21], v[28:29]
	v_pk_fma_f32 v[20:21], v[16:17], v[20:21], v[24:25]
	v_pk_fma_f32 v[22:23], v[16:17], v[22:23], v[34:35]
	s_waitcnt vmcnt(55)
	v_mov_b32_e32 v33, v66
	v_cvt_pk_bf16_f32 v30, v20, v21
	v_cvt_pk_bf16_f32 v31, v22, v23
	v_permlane32_swap_b32_e32 v66, v33
	v_cndmask_b32_e64 v32, v31, v30, s[0:1]
	global_store_dword v14, v32, s[8:9] offset:1024
	v_lshlrev_b32_e32 v26, 16, v66
	v_and_b32_e32 v27, 0xffff0000, v66
	v_lshlrev_b32_e32 v28, 16, v33
	v_and_b32_e32 v29, 0xffff0000, v33
	v_pk_fma_f32 v[24:25], v[18:19], v[22:23], v[26:27] neg_lo:[1,0,0] neg_hi:[1,0,0]
	v_pk_fma_f32 v[34:35], v[18:19], v[20:21], v[28:29]
	v_pk_fma_f32 v[20:21], v[16:17], v[20:21], v[24:25]
	v_pk_fma_f32 v[22:23], v[16:17], v[22:23], v[34:35]
	s_waitcnt vmcnt(55)
	v_mov_b32_e32 v33, v67
	v_cvt_pk_bf16_f32 v30, v20, v21
	v_cvt_pk_bf16_f32 v31, v22, v23
	v_permlane32_swap_b32_e32 v67, v33
	v_cndmask_b32_e64 v32, v31, v30, s[0:1]
	global_store_dword v14, v32, s[8:9] offset:0
	v_lshlrev_b32_e32 v26, 16, v67
	v_and_b32_e32 v27, 0xffff0000, v67
	v_lshlrev_b32_e32 v28, 16, v33
	v_and_b32_e32 v29, 0xffff0000, v33
	v_pk_fma_f32 v[24:25], v[18:19], v[22:23], v[26:27] neg_lo:[1,0,0] neg_hi:[1,0,0]
	v_pk_fma_f32 v[34:35], v[18:19], v[20:21], v[28:29]
	v_pk_fma_f32 v[20:21], v[16:17], v[20:21], v[24:25]
	v_pk_fma_f32 v[22:23], v[16:17], v[22:23], v[34:35]
	s_waitcnt vmcnt(55)
	v_mov_b32_e32 v33, v68
	v_cvt_pk_bf16_f32 v30, v20, v21
	v_cvt_pk_bf16_f32 v31, v22, v23
	v_permlane32_swap_b32_e32 v68, v33
	v_cndmask_b32_e64 v32, v31, v30, s[0:1]
	global_store_dword v14, v32, s[8:9] offset:-1024
	v_lshlrev_b32_e32 v26, 16, v68
	v_and_b32_e32 v27, 0xffff0000, v68
	v_lshlrev_b32_e32 v28, 16, v33
	v_and_b32_e32 v29, 0xffff0000, v33
	v_pk_fma_f32 v[24:25], v[18:19], v[22:23], v[26:27] neg_lo:[1,0,0] neg_hi:[1,0,0]
	v_pk_fma_f32 v[34:35], v[18:19], v[20:21], v[28:29]
	v_pk_fma_f32 v[20:21], v[16:17], v[20:21], v[24:25]
	v_pk_fma_f32 v[22:23], v[16:17], v[22:23], v[34:35]
	s_waitcnt vmcnt(55)
	v_mov_b32_e32 v33, v69
	v_cvt_pk_bf16_f32 v30, v20, v21
	v_cvt_pk_bf16_f32 v31, v22, v23
	v_permlane32_swap_b32_e32 v69, v33
	v_cndmask_b32_e64 v32, v31, v30, s[0:1]
	global_store_dword v14, v32, s[8:9] offset:-2048
	v_lshlrev_b32_e32 v26, 16, v69
	v_and_b32_e32 v27, 0xffff0000, v69
	v_lshlrev_b32_e32 v28, 16, v33
	v_and_b32_e32 v29, 0xffff0000, v33
	v_pk_fma_f32 v[24:25], v[18:19], v[22:23], v[26:27] neg_lo:[1,0,0] neg_hi:[1,0,0]
	v_pk_fma_f32 v[34:35], v[18:19], v[20:21], v[28:29]
	v_pk_fma_f32 v[20:21], v[16:17], v[20:21], v[24:25]
	v_pk_fma_f32 v[22:23], v[16:17], v[22:23], v[34:35]
	s_waitcnt vmcnt(55)
	v_mov_b32_e32 v33, v70
	v_cvt_pk_bf16_f32 v30, v20, v21
	v_cvt_pk_bf16_f32 v31, v22, v23
	v_permlane32_swap_b32_e32 v70, v33
	v_cndmask_b32_e64 v32, v31, v30, s[0:1]
	global_store_dword v14, v32, s[8:9] offset:-3072
	v_lshlrev_b32_e32 v26, 16, v70
	v_and_b32_e32 v27, 0xffff0000, v70
	v_lshlrev_b32_e32 v28, 16, v33
	v_and_b32_e32 v29, 0xffff0000, v33
	v_pk_fma_f32 v[24:25], v[18:19], v[22:23], v[26:27] neg_lo:[1,0,0] neg_hi:[1,0,0]
	v_pk_fma_f32 v[34:35], v[18:19], v[20:21], v[28:29]
	v_pk_fma_f32 v[20:21], v[16:17], v[20:21], v[24:25]
	v_pk_fma_f32 v[22:23], v[16:17], v[22:23], v[34:35]
	s_waitcnt vmcnt(55)
	v_mov_b32_e32 v33, v71
	v_cvt_pk_bf16_f32 v30, v20, v21
	v_cvt_pk_bf16_f32 v31, v22, v23
	v_permlane32_swap_b32_e32 v71, v33
	v_cndmask_b32_e64 v32, v31, v30, s[0:1]
	global_store_dword v14, v32, s[8:9] offset:-4096
	v_lshlrev_b32_e32 v26, 16, v71
	v_and_b32_e32 v27, 0xffff0000, v71
	v_lshlrev_b32_e32 v28, 16, v33
	v_and_b32_e32 v29, 0xffff0000, v33
	v_pk_fma_f32 v[24:25], v[18:19], v[22:23], v[26:27] neg_lo:[1,0,0] neg_hi:[1,0,0]
	v_pk_fma_f32 v[34:35], v[18:19], v[20:21], v[28:29]
	v_pk_fma_f32 v[20:21], v[16:17], v[20:21], v[24:25]
	v_pk_fma_f32 v[22:23], v[16:17], v[22:23], v[34:35]
	s_sub_u32 s8, s8, 0x2000
	s_subb_u32 s9, s9, 0
	s_sub_u32 s15, s15, 1
	s_cmp_lg_u32 s15, 0
	s_cbranch_scc1 .Lscan_loop_b
.Lscan_done:
	s_waitcnt vmcnt(0)
	s_mov_b64 s[6:7], exec
	s_branch .LBB0_114

; template <bool COOP>
; __global__ void __launch_bounds__(512, 2) fwd_kernel(Params p) {
;     ...
;     }
; }
.LBB0_641:
	s_nop 0
	s_nop 0
	s_nop 0
	s_nop 0
	s_nop 0
	s_nop 0
	s_nop 0
	s_nop 0
	s_nop 0
	s_nop 0
	s_nop 0
	s_nop 0
	s_nop 0
	s_nop 0
	s_nop 0
	s_nop 0
	s_nop 0
	s_nop 0
	s_nop 0
	s_nop 0
	s_nop 0
	s_nop 0
	s_nop 0
	s_nop 0
	s_nop 0
	s_nop 0
	s_nop 0
	s_nop 0
	s_nop 0
	s_nop 0
	s_nop 0
	s_nop 0
	s_nop 0
	s_nop 0
	s_nop 0
	s_nop 0
	s_nop 0
	s_nop 0
	s_nop 0
	s_nop 0
	s_nop 0
	s_nop 0
	s_nop 0
	s_nop 0
	s_nop 0
	s_nop 0
	s_nop 0
	s_nop 0
	s_nop 0
	s_nop 0
	s_nop 0
	s_nop 0
	s_nop 0
	s_nop 0
	s_nop 0
	s_nop 0
	s_nop 0
	s_nop 0
	s_nop 0
	s_nop 0
	s_nop 0
	s_nop 0
	s_nop 0
	s_nop 0
	s_nop 0
	s_nop 0
	s_nop 0
	s_nop 0
	s_nop 0
	s_nop 0
	s_nop 0
	s_nop 0
	s_nop 0
	s_nop 0
	s_nop 0
	s_nop 0
	s_nop 0
	s_nop 0
	s_nop 0
	s_nop 0
	s_nop 0
	s_nop 0
	s_nop 0
	s_nop 0
	s_nop 0
	s_nop 0
	s_nop 0
	s_nop 0
	s_nop 0
	s_nop 0
	s_nop 0
	s_nop 0
	s_nop 0
	s_nop 0
	s_nop 0
	s_nop 0
	s_nop 0
	s_nop 0
	s_nop 0
	s_nop 0
	s_nop 0
	s_nop 0
	s_nop 0
	s_nop 0
	s_nop 0
	s_nop 0
	s_nop 0
	s_nop 0
	s_nop 0
	s_nop 0
	s_nop 0
	s_nop 0
	s_nop 0
	s_nop 0
	s_nop 0
	s_nop 0
	s_nop 0
	s_nop 0
	s_nop 0
	s_nop 0
	s_nop 0
	s_nop 0
	s_nop 0
	s_nop 0
	s_nop 0
	s_endpgm
